# all validated LRU reductions combined: narrow h_fwd tiles + permlane32 swap + cl fold + conv-tap LDS layout + boundary-mask skip (on priority scheme + carry trims)
# speedup vs baseline: 1.0102x; 1.0102x over previous
; #define LAS __attribute__((address_space(3)))
; __device__ __forceinline__ int opaque_tid() { int t = threadIdx.x; asm volatile("" : "+v"(t)); return t; }
; template <int dir>
; __device__ __forceinline__ void lru_pass(LAS unsigned char* lds, const Params& P, int b, int h, int q, bool dry) {
;     ...
;     {
; #pragma unroll
;         for (int i = 0; i < 2; ++i) { const int idx = tid + i * NTHREADS, gate = idx >> 9, n = (idx >> 4) & 31, kc = idx & 15;
;             *(LAS u32x4*)(WB + (gate * 32 + n) * XC_PITCH + kc * 16) = *(const u32x4*)(LruW + ((size_t)((dir * 2 + gate) * 8 + h) * 128 + q * 32 + n) * 128 + kc * 8); }
;         const float br = -LOG2E * P.lru_ba[(dir * 8 + h) * 128 + chl], bi = -LOG2E * P.lru_bx[(dir * 8 + h) * 128 + chl];
;         const float lam = P.lru_lambda[dir * 1024 + ch];
;         const float cl = -8.0f * LOG2E * log1pf(__expf(-lam));
;         float carry = 0.f;
;         LruTile cur = lru_tile(Z, ZC, b, h, dir, 0);
;         u32x4 rows[11];
;         constexpr int NIN = dir == 0 ? 2 : 4;
;         u32x4 inr[NIN];
;         lru_load_rows(rows, cur, tr, cgp);
; __device__ __forceinline__ void lru_strip(LAS unsigned char* lds, const Params& P, int strip, bool dry) {
;     const int tid = opaque_tid();
;     const int b = strip >> 5, h = (strip >> 2) & 7, q = strip & 3;
;     LAS float* CWL = (LAS float*)(lds + 256 * XC_PITCH + 2048 + 64 * XC_PITCH);
;     for (int i = tid; i < 640; i += NTHREADS) { const int k = i >> 7, c = i & 127; CWL[i] = k < 4 ? P.conv_w[k * 1024 + h * 128 + c] : P.conv_b[h * 128 + c]; }
.LBB0_278:
	s_ashr_i32 s25, s2, 3
	v_mov_b32_e32 v128, v167
	s_bfe_u32 s26, s25, 0x30002
	s_lshl_b32 s27, s26, 7
	v_and_b32_e32 v204, 0x7f, v128
	v_or_b32_e32 v204, s27, v204
	v_lshrrev_b32_e32 v205, 7, v128
	v_lshl_or_b32 v205, v205, 10, v204
	v_lshlrev_b32_e32 v205, 2, v205
	v_lshlrev_b32_e32 v204, 2, v204
	global_load_dword v205, v205, s[52:53]
	global_load_dword v204, v204, s[54:55]
	v_readlane_b32 s0, v255, 19
	s_nop 3
	v_lshrrev_b32_e32 v206, 7, v128
	v_lshl_add_u32 v206, v206, 9, s0
	v_bfe_u32 v207, v128, 2, 1
	v_lshl_add_u32 v206, v207, 8, v206
	v_bfe_u32 v207, v128, 3, 4
	v_lshl_add_u32 v206, v207, 4, v206
	v_and_b32_e32 v207, 3, v128
	v_lshl_add_u32 v206, v207, 2, v206
	v_mov_b32_e32 v12, v167
	s_lshl_b32 s0, s25, 5
	s_and_b32 s28, s0, 0x60
	v_and_b32_e32 v15, 31, v12
	v_or_b32_e32 v17, s28, v15
	v_add_u32_e32 v14, 0x200, v12
	v_or_b32_e32 v11, s27, v17
	v_ashrrev_i32_e32 v8, 9, v12
	v_ashrrev_i32_e32 v10, 9, v14
	v_lshlrev_b32_e32 v16, 2, v11
	v_and_b32_e32 v13, 15, v12
	v_lshl_or_b32 v2, v8, 3, s26
	v_lshl_or_b32 v6, v10, 3, s26
	global_load_dword v18, v16, s[64:65]
	v_bfe_u32 v9, v12, 4, 5
	v_lshlrev_b32_e32 v64, 4, v13
	v_ashrrev_i32_e32 v3, 31, v2
	v_ashrrev_i32_e32 v7, 31, v6
	v_or_b32_e32 v4, s28, v9
	v_lshl_add_u64 v[0:1], s[38:39], 0, v[64:65]
	v_lshlrev_b64 v[2:3], 15, v[2:3]
	v_lshlrev_b64 v[6:7], 15, v[6:7]
	v_lshlrev_b32_e32 v4, 8, v4
	v_mov_b32_e32 v5, v65
	v_lshl_add_u64 v[2:3], v[0:1], 0, v[2:3]
	v_lshl_add_u64 v[0:1], v[0:1], 0, v[6:7]
	v_lshl_add_u64 v[2:3], v[2:3], 0, v[4:5]
	v_lshl_add_u64 v[4:5], v[0:1], 0, v[4:5]
	global_load_dwordx4 v[0:3], v[2:3], off
	s_nop 0
	global_load_dwordx4 v[4:7], v[4:5], off
	v_lshlrev_b32_e32 v11, 2, v12
	v_lshl_or_b32 v21, v8, 5, v9
	v_add_u32_e32 v8, s88, v64
	v_lshl_or_b32 v9, v10, 5, v9
	v_and_b32_e32 v22, 16, v11
	v_mad_u64_u32 v[10:11], s[4:5], v21, s89, v[8:9]
	v_mad_u64_u32 v[8:9], s[4:5], v9, s89, v[8:9]
	global_load_dword v9, v16, s[58:59]
	global_load_dword v11, v16, s[62:63]
	s_lshl_b32 s0, s2, 5
	s_and_b32 s0, s0, 0xe0
	s_or_b32 s1, s0, s25
	s_ashr_i32 s78, s1, 5
	s_ashr_i32 s79, s78, 31
	s_lshl_b32 s20, s26, 22
	s_lshl_b64 s[18:19], s[78:79], 19
	s_lshl_b64 s[44:45], s[78:79], 23
	v_readlane_b32 s1, v255, 18
	s_add_u32 s1, s1, s44
	s_addc_u32 s4, s33, s45
	s_lshl_b32 s5, s27, 2
	s_add_u32 s1, s1, s5
	s_addc_u32 s4, s4, 0
	s_add_u32 s5, s68, s18
	s_addc_u32 s6, s69, s19
	s_lshl_b32 s7, s27, 1
	s_add_u32 s48, s5, s7
	s_addc_u32 s49, s6, 0
	s_add_u32 s50, s48, 0x1000
	s_addc_u32 s51, s49, 0
	s_add_u32 s56, s48, 0x1800
	s_addc_u32 s57, s49, 0
	s_add_u32 s60, s48, 0x2000
	s_addc_u32 s61, s49, 0
	s_add_u32 s66, s48, 0x2800
	s_addc_u32 s67, s49, 0
	s_add_u32 s70, s48, 0x3000
	s_addc_u32 s71, s49, 0
	v_ashrrev_i32_e32 v36, 4, v12
	v_lshlrev_b32_e32 v37, 3, v13
	s_add_u32 s72, s48, 0x3800
	s_addc_u32 s73, s49, 0
	s_add_u32 s74, s48, 0x4000
	s_addc_u32 s75, s49, 0
	s_add_u32 s76, s48, 0x4800
	s_addc_u32 s77, s49, 0
	v_readfirstlane_b32 s0, v12
	s_ashr_i32 s6, s0, 6
	s_lshl_b32 s5, s28, 2
	s_add_u32 s8, s1, s5
	v_bfe_u32 v19, v12, 5, 1
	v_lshrrev_b32_e32 v20, 1, v12
	v_and_b32_e32 v33, 3, v12
	s_addc_u32 s9, s4, 0
	v_lshl_or_b32 v110, v36, 13, v37
	v_mov_b32_e32 v111, v65
	v_lshlrev_b64 v[110:111], 1, v[110:111]
	v_lshl_add_u64 v[108:109], s[48:49], 0, v[110:111]
	global_load_dwordx4 v[68:71], v[108:109], off offset:-2048
	global_load_dwordx4 v[72:75], v[108:109], off
	global_load_dwordx4 v[76:79], v[108:109], off offset:2048
	v_lshl_add_u64 v[108:109], s[50:51], 0, v[110:111]
	global_load_dwordx4 v[80:83], v[108:109], off
	v_lshl_add_u64 v[108:109], s[56:57], 0, v[110:111]
	global_load_dwordx4 v[84:87], v[108:109], off
	v_lshl_add_u64 v[108:109], s[60:61], 0, v[110:111]
	global_load_dwordx4 v[88:91], v[108:109], off
	v_lshl_add_u64 v[108:109], s[66:67], 0, v[110:111]
	global_load_dwordx4 v[92:95], v[108:109], off
	v_lshl_add_u64 v[108:109], s[70:71], 0, v[110:111]
	global_load_dwordx4 v[96:99], v[108:109], off
	v_lshl_add_u64 v[108:109], s[72:73], 0, v[110:111]
	global_load_dwordx4 v[100:103], v[108:109], off
	v_lshl_add_u64 v[108:109], s[74:75], 0, v[110:111]
	global_load_dwordx4 v[104:107], v[108:109], off
	v_lshl_add_u64 v[108:109], s[76:77], 0, v[110:111]
	global_load_dwordx4 v[108:111], v[108:109], off
	s_waitcnt vmcnt(14)
	ds_write_b128 v10, v[0:3]
	s_waitcnt vmcnt(13)
; #define LAS __attribute__((address_space(3)))
; template <int dir>
; __device__ __forceinline__ void lru_pass(LAS unsigned char* lds, const Params& P, int b, int h, int q, bool dry) {
;     ...
;         for (int i = 0; i < 2; ++i) { const int idx = tid + i * NTHREADS, gate = idx >> 9, n = (idx >> 4) & 31, kc = idx & 15;
;             *(LAS u32x4*)(WB + (gate * 32 + n) * XC_PITCH + kc * 16) = *(const u32x4*)(LruW + ((size_t)((dir * 2 + gate) * 8 + h) * 128 + q * 32 + n) * 128 + kc * 8); }
;         const float br = -LOG2E * P.lru_ba[(dir * 8 + h) * 128 + chl], bi = -LOG2E * P.lru_bx[(dir * 8 + h) * 128 + chl];
;         const float lam = P.lru_lambda[dir * 1024 + ch];
;         const float cl = -8.0f * LOG2E * log1pf(__expf(-lam));
; __device__ __forceinline__ void lru_strip(LAS unsigned char* lds, const Params& P, int strip, bool dry) {
;     ...
;     for (int i = tid; i < 640; i += NTHREADS) { const int k = i >> 7, c = i & 127; CWL[i] = k < 4 ? P.conv_w[k * 1024 + h * 128 + c] : P.conv_b[h * 128 + c]; }
	ds_write_b128 v8, v[4:7]
	ds_write_b32 v206, v205
	v_cmp_gt_u32_e32 vcc, 0x80, v128
	s_and_saveexec_b64 s[14:15], vcc
	ds_write_b32 v206, v204 offset:2048
	s_or_b64 exec, exec, s[14:15]
	v_mul_f32_e32 v16, 0xbfb8aa3b, v18
	v_exp_f32_e32 v16, v16
	s_lshl_b32 s1, s6, 5
	s_and_b32 s0, s0, 0x3fffffc0
	v_add_u32_e32 v39, 0, v64
	v_add_f32_e32 v2, 1.0, v16
	v_add_f32_e32 v3, -1.0, v2
	v_frexp_mant_f32_e32 v4, v2
	v_cvt_f64_f32_e32 v[0:1], v2
	v_sub_f32_e32 v5, v3, v2
	v_frexp_exp_i32_f64_e32 v0, v[0:1]
	v_cmp_gt_f32_e32 vcc, s80, v4
	v_sub_f32_e32 v3, v16, v3
	v_add_f32_e32 v1, 1.0, v5
	v_subbrev_co_u32_e32 v0, vcc, 0, v0, vcc
	v_add_f32_e32 v1, v3, v1
	v_sub_u32_e32 v3, 0, v0
	v_ldexp_f32 v2, v2, v3
	v_ldexp_f32 v1, v1, v3
	v_add_f32_e32 v3, -1.0, v2
	v_add_f32_e32 v4, 1.0, v2
	v_add_f32_e32 v5, 1.0, v3
	v_add_f32_e32 v6, -1.0, v4
	v_sub_f32_e32 v5, v2, v5
	v_sub_f32_e32 v2, v2, v6
	v_add_f32_e32 v5, v1, v5
	v_add_f32_e32 v1, v1, v2
	v_add_f32_e32 v6, v4, v1
	v_rcp_f32_e32 v7, v6
	v_add_f32_e32 v2, v3, v5
	v_sub_f32_e32 v4, v6, v4
	v_sub_f32_e32 v3, v2, v3
	v_sub_f32_e32 v1, v1, v4
	v_mul_f32_e32 v4, v2, v7
	v_sub_f32_e32 v3, v5, v3
	v_mul_f32_e32 v5, v6, v4
	v_fma_f32 v8, v4, v6, -v5
	v_fmac_f32_e32 v8, v4, v1
	v_add_f32_e32 v10, v5, v8
	v_sub_f32_e32 v18, v2, v10
	v_sub_f32_e32 v2, v2, v18
	v_sub_f32_e32 v5, v10, v5
	v_sub_f32_e32 v2, v2, v10
	v_sub_f32_e32 v5, v5, v8
	v_add_f32_e32 v2, v3, v2
	v_add_f32_e32 v2, v5, v2
	v_add_f32_e32 v3, v18, v2
	v_mul_f32_e32 v5, v7, v3
	v_mul_f32_e32 v10, v6, v5
	v_fma_f32 v6, v5, v6, -v10
	v_fmac_f32_e32 v6, v5, v1
	v_add_f32_e32 v1, v10, v6
	v_sub_f32_e32 v8, v18, v3
	v_sub_f32_e32 v18, v3, v1
	v_sub_f32_e32 v3, v3, v18
	v_add_f32_e32 v2, v2, v8
	v_sub_f32_e32 v10, v1, v10
	v_sub_f32_e32 v1, v3, v1
	v_sub_f32_e32 v6, v10, v6
	v_add_f32_e32 v1, v2, v1
	v_cvt_f32_i32_e32 v0, v0
	v_add_f32_e32 v8, v4, v5
	v_add_f32_e32 v1, v6, v1
	v_add_f32_e32 v1, v18, v1
	v_sub_f32_e32 v2, v8, v4
	v_mul_f32_e32 v1, v7, v1
	v_sub_f32_e32 v2, v5, v2
	v_add_f32_e32 v1, v2, v1
	v_mul_f32_e32 v5, 0x3f317218, v0
	v_add_f32_e32 v2, v8, v1
	v_fma_f32 v6, v0, s81, -v5
	v_fmac_f32_e32 v6, 0xb102e308, v0
	v_sub_f32_e32 v0, v2, v8
	v_mul_f32_e32 v3, v2, v2
	v_sub_f32_e32 v0, v1, v0
	v_add_f32_e32 v1, v5, v6
	v_fmamk_f32 v4, v3, 0x3e9b6dac, v200
	v_sub_f32_e32 v5, v1, v5
	v_fmaak_f32 v4, v3, v4, 0x3f2aaada
	v_sub_f32_e32 v5, v6, v5
	v_ldexp_f32 v6, v2, 1
	v_mul_f32_e32 v2, v2, v3
	v_mul_f32_e32 v2, v2, v4
	v_add_f32_e32 v3, v6, v2
	v_sub_f32_e32 v4, v3, v6
	v_ldexp_f32 v0, v0, 1
	v_sub_f32_e32 v2, v2, v4
	v_add_f32_e32 v0, v0, v2
	v_add_f32_e32 v2, v3, v0
	v_sub_f32_e32 v3, v2, v3
	v_sub_f32_e32 v0, v0, v3
	v_add_f32_e32 v3, v1, v2
	v_sub_f32_e32 v4, v3, v1
	v_sub_f32_e32 v6, v3, v4
	v_sub_f32_e32 v1, v1, v6
	v_sub_f32_e32 v2, v2, v4
	v_add_f32_e32 v1, v2, v1
	v_add_f32_e32 v2, v5, v0
	v_sub_f32_e32 v4, v2, v5
	v_add_f32_e32 v1, v2, v1
	v_sub_f32_e32 v6, v2, v4
	v_add_f32_e32 v2, v3, v1
	v_sub_f32_e32 v5, v5, v6
	v_sub_f32_e32 v0, v0, v4
	v_sub_f32_e32 v3, v2, v3
	v_add_f32_e32 v0, v0, v5
	v_sub_f32_e32 v1, v1, v3
	v_add_f32_e32 v0, v0, v1
	v_add_f32_e32 v0, v2, v0
	v_cmp_neq_f32_e32 vcc, s91, v16
	v_mov_b32_e32 v1, v65
	v_lshlrev_b32_e32 v41, 4, v19
	v_cndmask_b32_e32 v0, v201, v0, vcc
	v_cmp_ngt_f32_e32 vcc, -1.0, v16
	s_cmp_eq_u32 s6, 7
	v_or_b32_e32 v35, s1, v41
	v_cndmask_b32_e32 v0, v202, v0, vcc
	v_cmp_neq_f32_e32 vcc, -1.0, v16
	v_ashrrev_i32_e32 v32, 2, v12
	v_ashrrev_i32_e32 v34, 2, v14
	v_cndmask_b32_e32 v0, v203, v0, vcc
	v_cmp_lt_f32_e64 vcc, |v16|, s92
	v_lshlrev_b32_e32 v53, 4, v33
	v_mul_lo_u32 v48, v32, s87
	v_cndmask_b32_e32 v6, v0, v16, vcc
	v_lshlrev_b32_e32 v1, 2, v15
	v_lshlrev_b32_e32 v2, 4, v12
	v_add_u32_e32 v140, s94, v1
	v_and_b32_e32 v3, 48, v2
	v_and_b32_e32 v64, 0x70, v2
	v_and_or_b32 v2, v20, 12, v33
	v_or3_b32 v2, v2, v22, s1
	v_lshl_add_u32 v147, s0, 2, v140
	s_cselect_b64 s[0:1], -1, 0
	s_cmp_eq_u32 s6, 6
	s_cselect_b64 s[16:17], -1, 0
	s_cmp_eq_u32 s6, 5
	s_cselect_b64 s[4:5], -1, 0
	s_cmp_eq_u32 s6, 4
	v_lshl_add_u64 v[130:131], s[8:9], 0, v[64:65]
	s_cselect_b64 s[8:9], -1, 0
	s_cmp_eq_u32 s6, 3
	s_cselect_b64 s[10:11], -1, 0
	s_cmp_eq_u32 s6, 2
	s_cselect_b64 s[12:13], -1, 0
	s_cmp_eq_u32 s6, 1
	s_cselect_b64 s[14:15], -1, 0
	s_add_u32 s46, s20, s18
	s_addc_u32 s47, 0, s19
	s_lshl_b32 s6, s2, 3
	v_ashrrev_i32_e32 v33, 31, v32
	v_mul_lo_u32 v50, v35, s89
	v_mul_lo_u32 v51, v35, s87
	v_mul_lo_u32 v52, v35, s30
	v_ashrrev_i32_e32 v35, 31, v34
	s_bfe_u32 s29, s2, 0x20003
	s_and_b32 s6, s6, 0xc0
	v_lshlrev_b64 v[32:33], 8, v[32:33]
	v_mul_lo_u32 v2, v2, s89
	v_add_u32_e32 v46, s96, v1
	v_mul_lo_u32 v49, v34, s87
	v_add_u32_e32 v1, 0x400, v12
	v_lshlrev_b64 v[34:35], 8, v[34:35]
	v_lshl_add_u64 v[32:33], s[46:47], 0, v[32:33]
	s_add_u32 s18, s82, s46
	v_lshlrev_b32_e32 v38, 4, v13
	v_add_u32_e32 v129, s96, v64
	v_add_u32_e32 v42, 0, v2
	v_mov_b32_e32 v2, s88
	v_ashrrev_i32_e32 v143, 3, v1
	v_add_u32_e32 v1, 0x600, v12
	v_lshl_add_u64 v[34:35], s[46:47], 0, v[34:35]
	v_or3_b32 v32, v32, s6, v53
	v_lshl_or_b32 v64, v36, 10, v37
	s_addc_u32 s19, s83, s47
	v_mov_b32_e32 v66, v65
	v_mov_b32_e32 v67, v65
	s_waitcnt vmcnt(12)
; template <int dir>
; __device__ __forceinline__ void lru_pass(LAS unsigned char* lds, const Params& P, int b, int h, int q, bool dry) {
;     ...
;         const float br = -LOG2E * P.lru_ba[(dir * 8 + h) * 128 + chl], bi = -LOG2E * P.lru_bx[(dir * 8 + h) * 128 + chl];
;         const float lam = P.lru_lambda[dir * 1024 + ch];
;         const float cl = -8.0f * LOG2E * log1pf(__expf(-lam));
;         float carry = 0.f;
;         LruTile cur = lru_tile(Z, ZC, b, h, dir, 0);
;         u32x4 rows[11];
;         constexpr int NIN = dir == 0 ? 2 : 4;
;         u32x4 inr[NIN];
;         lru_load_rows(rows, cur, tr, cgp);
; #pragma unroll
;         for (int i = 0; i < NIN; ++i) inr[i] = (u32x4){0u, 0u, 0u, 0u};
;         int t0_prev = 0;
;     ...
;             f32x16 zr, zi;
; #pragma unroll
;             for (int v = 0; v < 16; ++v) { zr[v] = br; zi[v] = bi; }
;             const int sbase = 32 * wid + 16 * g;
;             { const int sl = 32 * wid + s_i; const int tlA = dir == 0 ? sl : 255 - sl;
	v_mul_f32_e32 v0, 0xbfb8aa3b, v9
	s_waitcnt vmcnt(11)
	v_mul_f32_e32 v16, 0xbfb8aa3b, v11
	v_add_u32_e32 v40, s95, v3
	v_mad_u32_u24 v43, v15, s89, v2
	v_lshl_add_u32 v44, v17, 1, 0
	v_lshl_add_u32 v45, v15, 1, s95
	v_mul_lo_u32 v47, v36, s93
	v_ashrrev_i32_e32 v148, 3, v12
	v_ashrrev_i32_e32 v145, 3, v14
	v_ashrrev_i32_e32 v141, 3, v1
	v_or3_b32 v34, v34, s6, v53
	v_lshl_add_u64 v[134:135], s[40:41], 0, v[32:33]
	v_lshl_add_u64 v[136:137], v[64:65], 1, s[18:19]
	v_mov_b32_e32 v64, v65
	v_add_u32_e32 v32, 0, v38
	v_mov_b64_e32 v[114:115], v[66:67]
	v_mov_b64_e32 v[118:119], v[66:67]
	s_mov_b32 s90, 0
	v_mul_f32_e32 v138, 0xc138aa3b, v6
	v_rcp_f32_e32 v138, v138
	s_nop 0
	v_lshl_add_u32 v139, v36, 3, -1
	v_cmp_eq_u32_e32 vcc, 0, v19
	v_mul_lo_u32 v149, v148, s30
	v_mul_lo_u32 v146, v145, s30
	v_mul_lo_u32 v144, v143, s30
	v_mul_lo_u32 v142, v141, s30
	v_mov_b32_e32 v1, v0
	v_mov_b32_e32 v2, v0
	v_mov_b32_e32 v3, v0
	v_mov_b32_e32 v4, v0
	v_mov_b32_e32 v5, v0
	v_mov_b32_e32 v6, v0
	v_mov_b32_e32 v7, v0
	v_mov_b32_e32 v8, v0
	v_mov_b32_e32 v9, v0
	v_mov_b32_e32 v10, v0
	v_mov_b32_e32 v11, v0
	v_mov_b32_e32 v12, v0
	v_mov_b32_e32 v13, v0
	v_mov_b32_e32 v14, v0
	v_mov_b32_e32 v15, v0
	v_mov_b32_e32 v17, v16
	v_mov_b32_e32 v18, v16
	v_mov_b32_e32 v19, v16
	v_mov_b32_e32 v20, v16
	v_mov_b32_e32 v21, v16
	v_mov_b32_e32 v22, v16
	v_mov_b32_e32 v23, v16
	v_mov_b32_e32 v24, v16
	v_mov_b32_e32 v25, v16
	v_mov_b32_e32 v26, v16
	v_mov_b32_e32 v27, v16
	v_mov_b32_e32 v28, v16
	v_mov_b32_e32 v29, v16
	v_mov_b32_e32 v30, v16
	v_mov_b32_e32 v31, v16
	v_lshl_add_u64 v[132:133], s[40:41], 0, v[34:35]
	s_movk_i32 s92, 0x100
	v_mov_b32_e32 v165, 0
	s_mov_b64 s[80:81], 0
	v_add_u32_e32 v150, 0x15c00, v32
	v_add_u32_e32 v151, v39, v47
	v_add_u32_e32 v158, v40, v48
	v_add_u32_e32 v159, v40, v49
	v_add_u32_e32 v160, v42, v41
	v_add_u32_e32 v161, v43, v41
	v_add_u32_e32 v162, v44, v50
	v_add_u32_e32 v163, v45, v51
	v_add_u32_e32 v164, v46, v52
	v_mov_b64_e32 v[112:113], v[64:65]
	v_mov_b64_e32 v[116:117], v[64:65]
	s_mov_b32 s91, 0
	s_mov_b32 s93, 0
	s_mov_b32 s97, 0
	v_lshrrev_b32_e32 v254, 8, v167
	v_mul_u32_u24_e32 v252, 0x1400, v254
	v_add_u32_e32 v158, v158, v252
	v_add_u32_e32 v159, v159, v252
	v_add_u32_e32 v159, 0xffffec00, v159
	v_lshlrev_b32_e32 v252, 14, v254
	v_mov_b32_e32 v253, 0
	v_lshl_add_u64 v[134:135], v[252:253], 0, v[134:135]
	v_lshl_add_u64 v[132:133], v[252:253], 0, v[132:133]
	s_mov_b32 s18, 0xffffc000
	s_mov_b32 s19, -1
	v_lshl_add_u64 v[132:133], v[132:133], 0, s[18:19]
	v_mul_u32_u24_e32 v252, 0x3600, v254
	v_add_u32_e32 v149, v149, v252
	v_add_u32_e32 v146, v146, v252
	v_add_u32_e32 v144, v144, v252
	v_add_u32_e32 v142, v142, v252
	v_add_u32_e32 v146, 0xffffee00, v146
	v_add_u32_e32 v144, 0xffffdc00, v144
	v_add_u32_e32 v142, 0xffffca00, v142
	v_mul_u32_u24_e32 v252, 0x60, v254
	v_add_u32_e32 v148, v148, v252
	v_add_u32_e32 v145, v145, v252
	v_add_u32_e32 v143, v143, v252
	v_add_u32_e32 v141, v141, v252
	v_add_u32_e32 v145, 0xffffffe0, v145
	v_add_u32_e32 v143, 0xffffffc0, v143
	v_add_u32_e32 v141, 0xffffffa0, v141
	v_lshrrev_b32_e32 v253, 6, v167
	s_nop 1
	v_readfirstlane_b32 s18, v253
	s_lshr_b32 s101, s18, 2
	s_or_b32 s19, s18, 4
	s_cmp_eq_u32 s19, 7
	s_cselect_b64 s[0:1], -1, 0
	s_cmp_eq_u32 s19, 6
	s_cselect_b64 s[16:17], -1, 0
	s_cmp_eq_u32 s19, 5
	s_cselect_b64 s[4:5], -1, 0
	s_cmp_eq_u32 s19, 4
	s_cselect_b64 s[8:9], -1, 0
	s_mov_b64 s[10:11], 0
	s_mov_b64 s[12:13], 0
	s_mov_b64 s[14:15], 0
	v_and_b32_e32 v252, 31, v167
	v_lshlrev_b32_e32 v253, 2, v252
	v_sub_u32_e32 v164, v164, v253
	v_subrev_u32_e32 v164, s96, v164
	v_mul_u32_u24_e32 v164, 0x1c8, v164
	v_lshrrev_b32_e32 v164, 16, v164
	v_mul_u32_u24_e32 v164, 0x50, v164
	v_lshl_add_u32 v164, v252, 1, v164
	v_add_u32_e32 v164, s95, v164
	s_mov_b32 s98, 0
	s_cmp_eq_u32 s101, 0
	s_cselect_b32 s99, 0x14400, 0
	s_cselect_b32 s100, 0, 0x400
	v_add_u32_e32 v253, 0x14000, v147
	v_mov_b32_e32 v254, 1.0
	v_mov_b32_e32 v252, 0
	ds_write2_b32 v253, v254, v252 offset1:32
	s_waitcnt lgkmcnt(0)
	s_barrier
	s_cmp_eq_u32 s101, 0
	s_cbranch_scc1 .Lpp_f_nox
	s_barrier

; #define LAS __attribute__((address_space(3)))
; __device__ __forceinline__ unsigned cvt_pk_bf16(float lo, float hi) { unsigned r; asm volatile("v_cvt_pk_bf16_f32 %0, %1, %2" : "=v"(r) : "v"(lo), "v"(hi)); return r; }
; __device__ __forceinline__ float bf_lo(unsigned u) { return __uint_as_float(u << 16); }
; __device__ __forceinline__ float bf_hi(unsigned u) { return __uint_as_float(u & 0xffff0000u); }
; template <int dir>
; __device__ __forceinline__ void lru_pass(LAS unsigned char* lds, const Params& P, int b, int h, int q, bool dry) {
;     ...
;             f32x2 cw2[4][4], cb2[4];
; #pragma unroll
;             for (int k = 0; k < 5; ++k) { const f32x4 a = *(const LAS f32x4*)(CWL + k * 128 + cgp * 8), c2 = *(const LAS f32x4*)(CWL + k * 128 + cgp * 8 + 4);
;                 if (k < 4) { cw2[k][0] = (f32x2){a[0], a[1]}; cw2[k][1] = (f32x2){a[2], a[3]}; cw2[k][2] = (f32x2){c2[0], c2[1]}; cw2[k][3] = (f32x2){c2[2], c2[3]}; }
;                 else { cb2[0] = (f32x2){a[0], a[1]}; cb2[1] = (f32x2){a[2], a[3]}; cb2[2] = (f32x2){c2[0], c2[1]}; cb2[3] = (f32x2){c2[2], c2[3]}; } }
; #pragma unroll
;             for (int j = 0; j < 8; ++j) {
;                 f32x2 o0 = cb2[0], o1 = cb2[1], o2 = cb2[2], o3 = cb2[3];
; #pragma unroll
;                 for (int k = 0; k < 4; ++k) { const u32x4 rr = rows[j + k];
;                     o0 = cw2[k][0] * (f32x2){bf_lo(rr.x), bf_hi(rr.x)} + o0; o1 = cw2[k][1] * (f32x2){bf_lo(rr.y), bf_hi(rr.y)} + o1;
;                     o2 = cw2[k][2] * (f32x2){bf_lo(rr.z), bf_hi(rr.z)} + o2; o3 = cw2[k][3] * (f32x2){bf_lo(rr.w), bf_hi(rr.w)} + o3; }
;                 u32x4 w; w.x = cvt_pk_bf16(o0[0], o0[1]); w.y = cvt_pk_bf16(o1[0], o1[1]); w.z = cvt_pk_bf16(o2[0], o2[1]); w.w = cvt_pk_bf16(o3[0], o3[1]);
;                 *(LAS u32x4*)(XC + (tr * 8 + j) * XC_PITCH + cgp * 16) = w;
;             }
.Lmsk_f_j:
	ds_read_b128 v[60:63], v150
	ds_read_b128 v[52:55], v150 offset:256
	ds_read_b128 v[44:47], v150 offset:768
	ds_read_b128 v[56:59], v150 offset:512
	ds_read_b128 v[40:43], v150 offset:1280
	ds_read_b128 v[48:51], v150 offset:1024
	ds_read_b128 v[120:123], v150 offset:2304
	ds_read_b128 v[124:127], v150 offset:2048
	ds_read_b128 v[32:35], v150 offset:1792
	ds_read_b128 v[36:39], v150 offset:1536
	v_lshlrev_b32_e32 v66, 16, v68
	v_and_b32_e32 v67, 0xffff0000, v68
	v_lshlrev_b32_e32 v154, 16, v69
	v_and_b32_e32 v155, 0xffff0000, v69
	v_lshlrev_b32_e32 v168, 16, v70
	v_and_b32_e32 v169, 0xffff0000, v70
	s_waitcnt lgkmcnt(2)
	v_pk_fma_f32 v[66:67], v[60:61], v[66:67], v[124:125]
	v_pk_fma_f32 v[154:155], v[62:63], v[154:155], v[126:127]
	v_pk_fma_f32 v[168:169], v[52:53], v[168:169], v[120:121]
	v_lshlrev_b32_e32 v170, 16, v71
	v_and_b32_e32 v171, 0xffff0000, v71
	v_lshlrev_b32_e32 v172, 16, v72
	v_and_b32_e32 v173, 0xffff0000, v72
	v_lshlrev_b32_e32 v174, 16, v73
	v_and_b32_e32 v175, 0xffff0000, v73
	v_lshlrev_b32_e32 v176, 16, v74
	v_and_b32_e32 v177, 0xffff0000, v74
	v_pk_fma_f32 v[170:171], v[54:55], v[170:171], v[122:123]
	v_pk_fma_f32 v[66:67], v[56:57], v[172:173], v[66:67]
	v_pk_fma_f32 v[154:155], v[58:59], v[174:175], v[154:155]
	v_pk_fma_f32 v[168:169], v[44:45], v[176:177], v[168:169]
	v_lshlrev_b32_e32 v178, 16, v75
	v_and_b32_e32 v179, 0xffff0000, v75
	v_lshlrev_b32_e32 v180, 16, v76
	v_and_b32_e32 v181, 0xffff0000, v76
	v_lshlrev_b32_e32 v182, 16, v77
	v_and_b32_e32 v183, 0xffff0000, v77
	v_lshlrev_b32_e32 v184, 16, v78
	v_and_b32_e32 v185, 0xffff0000, v78
	v_pk_fma_f32 v[170:171], v[46:47], v[178:179], v[170:171]
	v_pk_fma_f32 v[66:67], v[48:49], v[180:181], v[66:67]
	v_pk_fma_f32 v[154:155], v[50:51], v[182:183], v[154:155]
	v_pk_fma_f32 v[168:169], v[40:41], v[184:185], v[168:169]
	v_lshlrev_b32_e32 v186, 16, v79
	v_and_b32_e32 v187, 0xffff0000, v79
	v_lshlrev_b32_e32 v188, 16, v80
	v_and_b32_e32 v189, 0xffff0000, v80
	v_lshlrev_b32_e32 v190, 16, v81
	v_and_b32_e32 v191, 0xffff0000, v81
	v_lshlrev_b32_e32 v192, 16, v82
	v_and_b32_e32 v193, 0xffff0000, v82
	v_pk_fma_f32 v[170:171], v[42:43], v[186:187], v[170:171]
	s_waitcnt lgkmcnt(0)
	v_pk_fma_f32 v[66:67], v[36:37], v[188:189], v[66:67]
	v_pk_fma_f32 v[154:155], v[38:39], v[190:191], v[154:155]
	v_pk_fma_f32 v[194:195], v[32:33], v[192:193], v[168:169]
	v_lshlrev_b32_e32 v196, 16, v83
	v_and_b32_e32 v197, 0xffff0000, v83
	v_cvt_pk_bf16_f32 v168, v66, v67
	v_cvt_pk_bf16_f32 v169, v154, v155
	v_pk_fma_f32 v[198:199], v[34:35], v[196:197], v[170:171]
	v_cvt_pk_bf16_f32 v170, v194, v195
	v_pk_fma_f32 v[66:67], v[60:61], v[172:173], v[124:125]
	v_cvt_pk_bf16_f32 v171, v198, v199
	ds_write_b128 v151, v[168:171]
	v_pk_fma_f32 v[154:155], v[62:63], v[174:175], v[126:127]
	v_pk_fma_f32 v[168:169], v[52:53], v[176:177], v[120:121]
	v_pk_fma_f32 v[170:171], v[54:55], v[178:179], v[122:123]
	v_pk_fma_f32 v[66:67], v[56:57], v[180:181], v[66:67]
	v_pk_fma_f32 v[154:155], v[58:59], v[182:183], v[154:155]
	v_pk_fma_f32 v[168:169], v[44:45], v[184:185], v[168:169]
	v_pk_fma_f32 v[170:171], v[46:47], v[186:187], v[170:171]
	v_pk_fma_f32 v[66:67], v[48:49], v[188:189], v[66:67]
	v_pk_fma_f32 v[154:155], v[50:51], v[190:191], v[154:155]
	v_pk_fma_f32 v[168:169], v[40:41], v[192:193], v[168:169]
	v_lshlrev_b32_e32 v172, 16, v84
	v_and_b32_e32 v173, 0xffff0000, v84
	v_lshlrev_b32_e32 v174, 16, v85
	v_and_b32_e32 v175, 0xffff0000, v85
	v_lshlrev_b32_e32 v176, 16, v86
	v_and_b32_e32 v177, 0xffff0000, v86
	v_pk_fma_f32 v[170:171], v[42:43], v[196:197], v[170:171]
	v_pk_fma_f32 v[66:67], v[36:37], v[172:173], v[66:67]
	v_pk_fma_f32 v[154:155], v[38:39], v[174:175], v[154:155]
	v_pk_fma_f32 v[178:179], v[32:33], v[176:177], v[168:169]
	v_lshlrev_b32_e32 v194, 16, v87
	v_and_b32_e32 v195, 0xffff0000, v87
	v_cvt_pk_bf16_f32 v168, v66, v67
	v_cvt_pk_bf16_f32 v169, v154, v155
	v_pk_fma_f32 v[198:199], v[34:35], v[194:195], v[170:171]
	v_cvt_pk_bf16_f32 v170, v178, v179
	v_pk_fma_f32 v[66:67], v[60:61], v[180:181], v[124:125]
	v_cvt_pk_bf16_f32 v171, v198, v199
	ds_write_b128 v151, v[168:171] offset:272
	v_pk_fma_f32 v[154:155], v[62:63], v[182:183], v[126:127]
	v_pk_fma_f32 v[168:169], v[52:53], v[184:185], v[120:121]
	v_pk_fma_f32 v[170:171], v[54:55], v[186:187], v[122:123]
	v_pk_fma_f32 v[66:67], v[56:57], v[188:189], v[66:67]
	v_pk_fma_f32 v[154:155], v[58:59], v[190:191], v[154:155]
	v_pk_fma_f32 v[168:169], v[44:45], v[192:193], v[168:169]
	v_pk_fma_f32 v[170:171], v[46:47], v[196:197], v[170:171]
	v_pk_fma_f32 v[66:67], v[48:49], v[172:173], v[66:67]
	v_pk_fma_f32 v[154:155], v[50:51], v[174:175], v[154:155]
	v_pk_fma_f32 v[168:169], v[40:41], v[176:177], v[168:169]
	v_lshlrev_b32_e32 v178, 16, v88
	v_and_b32_e32 v179, 0xffff0000, v88
	v_lshlrev_b32_e32 v180, 16, v89
	v_and_b32_e32 v181, 0xffff0000, v89
	v_lshlrev_b32_e32 v182, 16, v90
	v_and_b32_e32 v183, 0xffff0000, v90
	v_pk_fma_f32 v[170:171], v[42:43], v[194:195], v[170:171]
	v_pk_fma_f32 v[66:67], v[36:37], v[178:179], v[66:67]
	v_pk_fma_f32 v[154:155], v[38:39], v[180:181], v[154:155]
	v_pk_fma_f32 v[184:185], v[32:33], v[182:183], v[168:169]
	v_lshlrev_b32_e32 v186, 16, v91
	v_and_b32_e32 v187, 0xffff0000, v91
	v_cvt_pk_bf16_f32 v168, v66, v67
	v_cvt_pk_bf16_f32 v169, v154, v155
	v_pk_fma_f32 v[198:199], v[34:35], v[186:187], v[170:171]
	v_cvt_pk_bf16_f32 v170, v184, v185
	v_pk_fma_f32 v[66:67], v[60:61], v[188:189], v[124:125]
	v_cvt_pk_bf16_f32 v171, v198, v199
	ds_write_b128 v151, v[168:171] offset:544
	v_pk_fma_f32 v[154:155], v[62:63], v[190:191], v[126:127]
	v_pk_fma_f32 v[168:169], v[52:53], v[192:193], v[120:121]
; #define LAS __attribute__((address_space(3)))
; __device__ __forceinline__ unsigned cvt_pk_bf16(float lo, float hi) { unsigned r; asm volatile("v_cvt_pk_bf16_f32 %0, %1, %2" : "=v"(r) : "v"(lo), "v"(hi)); return r; }
; __device__ __forceinline__ float bf_lo(unsigned u) { return __uint_as_float(u << 16); }
; __device__ __forceinline__ float bf_hi(unsigned u) { return __uint_as_float(u & 0xffff0000u); }
; template <int dir>
; __device__ __forceinline__ void lru_pass(LAS unsigned char* lds, const Params& P, int b, int h, int q, bool dry) {
;     ...
;             for (int j = 0; j < 11; ++j) { if (j != 0 && j < 9) continue;
;                 const int t = t0 + tr * 8 - 1 + j; if (t < 0 || t >= cur.L) rows[j] = (u32x4){0u, 0u, 0u, 0u}; }
;             f32x2 cw2[4][4], cb2[4];
; #pragma unroll
;             for (int k = 0; k < 5; ++k) { const f32x4 a = *(const LAS f32x4*)(CWL + k * 128 + cgp * 8), c2 = *(const LAS f32x4*)(CWL + k * 128 + cgp * 8 + 4);
;                 if (k < 4) { cw2[k][0] = (f32x2){a[0], a[1]}; cw2[k][1] = (f32x2){a[2], a[3]}; cw2[k][2] = (f32x2){c2[0], c2[1]}; cw2[k][3] = (f32x2){c2[2], c2[3]}; }
;                 else { cb2[0] = (f32x2){a[0], a[1]}; cb2[1] = (f32x2){a[2], a[3]}; cb2[2] = (f32x2){c2[0], c2[1]}; cb2[3] = (f32x2){c2[2], c2[3]}; } }
; #pragma unroll
;             for (int j = 0; j < 8; ++j) {
;                 f32x2 o0 = cb2[0], o1 = cb2[1], o2 = cb2[2], o3 = cb2[3];
; #pragma unroll
;                 for (int k = 0; k < 4; ++k) { const u32x4 rr = rows[j + k];
;                     o0 = cw2[k][0] * (f32x2){bf_lo(rr.x), bf_hi(rr.x)} + o0; o1 = cw2[k][1] * (f32x2){bf_lo(rr.y), bf_hi(rr.y)} + o1;
;                     o2 = cw2[k][2] * (f32x2){bf_lo(rr.z), bf_hi(rr.z)} + o2; o3 = cw2[k][3] * (f32x2){bf_lo(rr.w), bf_hi(rr.w)} + o3; }
;                 u32x4 w; w.x = cvt_pk_bf16(o0[0], o0[1]); w.y = cvt_pk_bf16(o1[0], o1[1]); w.z = cvt_pk_bf16(o2[0], o2[1]); w.w = cvt_pk_bf16(o3[0], o3[1]);
;                 *(LAS u32x4*)(XC + (tr * 8 + j) * XC_PITCH + cgp * 16) = w;
;             }
	v_pk_fma_f32 v[170:171], v[54:55], v[196:197], v[122:123]
	v_pk_fma_f32 v[66:67], v[56:57], v[172:173], v[66:67]
	v_pk_fma_f32 v[154:155], v[58:59], v[174:175], v[154:155]
	v_pk_fma_f32 v[168:169], v[44:45], v[176:177], v[168:169]
	v_pk_fma_f32 v[170:171], v[46:47], v[194:195], v[170:171]
	v_pk_fma_f32 v[66:67], v[48:49], v[178:179], v[66:67]
	v_pk_fma_f32 v[154:155], v[50:51], v[180:181], v[154:155]
	v_pk_fma_f32 v[168:169], v[40:41], v[182:183], v[168:169]
	v_lshlrev_b32_e32 v184, 16, v92
	v_and_b32_e32 v185, 0xffff0000, v92
	v_lshlrev_b32_e32 v188, 16, v93
	v_and_b32_e32 v189, 0xffff0000, v93
	v_lshlrev_b32_e32 v190, 16, v94
	v_and_b32_e32 v191, 0xffff0000, v94
	v_pk_fma_f32 v[170:171], v[42:43], v[186:187], v[170:171]
	v_pk_fma_f32 v[66:67], v[36:37], v[184:185], v[66:67]
	v_pk_fma_f32 v[154:155], v[38:39], v[188:189], v[154:155]
	v_pk_fma_f32 v[192:193], v[32:33], v[190:191], v[168:169]
	v_lshlrev_b32_e32 v196, 16, v95
	v_and_b32_e32 v197, 0xffff0000, v95
	v_cvt_pk_bf16_f32 v168, v66, v67
	v_cvt_pk_bf16_f32 v169, v154, v155
	v_pk_fma_f32 v[198:199], v[34:35], v[196:197], v[170:171]
	v_cvt_pk_bf16_f32 v170, v192, v193
	v_pk_fma_f32 v[66:67], v[60:61], v[172:173], v[124:125]
	v_cvt_pk_bf16_f32 v171, v198, v199
	ds_write_b128 v151, v[168:171] offset:816
	v_pk_fma_f32 v[154:155], v[62:63], v[174:175], v[126:127]
	v_pk_fma_f32 v[168:169], v[52:53], v[176:177], v[120:121]
	v_pk_fma_f32 v[170:171], v[54:55], v[194:195], v[122:123]
	v_pk_fma_f32 v[66:67], v[56:57], v[178:179], v[66:67]
	v_pk_fma_f32 v[154:155], v[58:59], v[180:181], v[154:155]
	v_pk_fma_f32 v[168:169], v[44:45], v[182:183], v[168:169]
	v_pk_fma_f32 v[170:171], v[46:47], v[186:187], v[170:171]
	v_pk_fma_f32 v[66:67], v[48:49], v[184:185], v[66:67]
	v_pk_fma_f32 v[154:155], v[50:51], v[188:189], v[154:155]
	v_pk_fma_f32 v[168:169], v[40:41], v[190:191], v[168:169]
	v_lshlrev_b32_e32 v172, 16, v96
	v_and_b32_e32 v173, 0xffff0000, v96
	v_lshlrev_b32_e32 v174, 16, v97
	v_and_b32_e32 v175, 0xffff0000, v97
	v_lshlrev_b32_e32 v176, 16, v98
	v_and_b32_e32 v177, 0xffff0000, v98
	v_pk_fma_f32 v[170:171], v[42:43], v[196:197], v[170:171]
	v_pk_fma_f32 v[66:67], v[36:37], v[172:173], v[66:67]
	v_pk_fma_f32 v[154:155], v[38:39], v[174:175], v[154:155]
	v_pk_fma_f32 v[192:193], v[32:33], v[176:177], v[168:169]
	v_lshlrev_b32_e32 v194, 16, v99
	v_and_b32_e32 v195, 0xffff0000, v99
	v_cvt_pk_bf16_f32 v168, v66, v67
	v_cvt_pk_bf16_f32 v169, v154, v155
	v_pk_fma_f32 v[198:199], v[34:35], v[194:195], v[170:171]
	v_cvt_pk_bf16_f32 v170, v192, v193
	v_pk_fma_f32 v[66:67], v[60:61], v[178:179], v[124:125]
	v_cvt_pk_bf16_f32 v171, v198, v199
	ds_write_b128 v151, v[168:171] offset:1088
	v_pk_fma_f32 v[154:155], v[62:63], v[180:181], v[126:127]
	v_pk_fma_f32 v[168:169], v[52:53], v[182:183], v[120:121]
	v_pk_fma_f32 v[170:171], v[54:55], v[186:187], v[122:123]
	v_pk_fma_f32 v[66:67], v[56:57], v[184:185], v[66:67]
	v_pk_fma_f32 v[154:155], v[58:59], v[188:189], v[154:155]
	v_pk_fma_f32 v[168:169], v[44:45], v[190:191], v[168:169]
	v_pk_fma_f32 v[170:171], v[46:47], v[196:197], v[170:171]
	v_pk_fma_f32 v[66:67], v[48:49], v[172:173], v[66:67]
	v_pk_fma_f32 v[154:155], v[50:51], v[174:175], v[154:155]
	v_pk_fma_f32 v[168:169], v[40:41], v[176:177], v[168:169]
	v_lshlrev_b32_e32 v178, 16, v100
	v_and_b32_e32 v179, 0xffff0000, v100
	v_lshlrev_b32_e32 v180, 16, v101
	v_and_b32_e32 v181, 0xffff0000, v101
	v_lshlrev_b32_e32 v182, 16, v102
	v_and_b32_e32 v183, 0xffff0000, v102
	v_pk_fma_f32 v[170:171], v[42:43], v[194:195], v[170:171]
	v_pk_fma_f32 v[66:67], v[36:37], v[178:179], v[66:67]
	v_pk_fma_f32 v[154:155], v[38:39], v[180:181], v[154:155]
	v_pk_fma_f32 v[186:187], v[32:33], v[182:183], v[168:169]
	v_lshlrev_b32_e32 v192, 16, v103
	v_and_b32_e32 v193, 0xffff0000, v103
	v_cvt_pk_bf16_f32 v168, v66, v67
	v_cvt_pk_bf16_f32 v169, v154, v155
	s_and_b64 s[18:19], s[18:19], s[20:21]
	v_pk_fma_f32 v[198:199], v[34:35], v[192:193], v[170:171]
	v_cvt_pk_bf16_f32 v170, v186, v187
	v_pk_fma_f32 v[66:67], v[60:61], v[184:185], v[124:125]
	v_cvt_pk_bf16_f32 v171, v198, v199
	ds_write_b128 v151, v[168:171] offset:1360
	v_pk_fma_f32 v[168:169], v[52:53], v[190:191], v[120:121]
	v_pk_fma_f32 v[60:61], v[60:61], v[172:173], v[124:125]
	v_pk_fma_f32 v[52:53], v[52:53], v[176:177], v[120:121]
	s_waitcnt vmcnt(0)
	v_cndmask_b32_e64 v108, 0, v108, s[18:19]
	v_pk_fma_f32 v[154:155], v[62:63], v[188:189], v[126:127]
	v_pk_fma_f32 v[66:67], v[56:57], v[172:173], v[66:67]
	v_pk_fma_f32 v[168:169], v[44:45], v[176:177], v[168:169]
	v_lshlrev_b32_e32 v184, 16, v104
	v_and_b32_e32 v185, 0xffff0000, v104
	v_lshlrev_b32_e32 v188, 16, v106
	v_and_b32_e32 v189, 0xffff0000, v106
	v_pk_fma_f32 v[62:63], v[62:63], v[174:175], v[126:127]
	v_pk_fma_f32 v[56:57], v[56:57], v[178:179], v[60:61]
	v_pk_fma_f32 v[44:45], v[44:45], v[182:183], v[52:53]
	v_cndmask_b32_e64 v109, 0, v109, s[18:19]
	v_pk_fma_f32 v[154:155], v[58:59], v[174:175], v[154:155]
	v_pk_fma_f32 v[66:67], v[48:49], v[178:179], v[66:67]
	v_pk_fma_f32 v[168:169], v[40:41], v[182:183], v[168:169]
	v_lshlrev_b32_e32 v186, 16, v105
	v_and_b32_e32 v187, 0xffff0000, v105
	v_pk_fma_f32 v[58:59], v[58:59], v[180:181], v[62:63]
	v_pk_fma_f32 v[48:49], v[48:49], v[184:185], v[56:57]
	v_pk_fma_f32 v[40:41], v[40:41], v[188:189], v[44:45]
	v_lshlrev_b32_e32 v44, 16, v108
	v_and_b32_e32 v45, 0xffff0000, v108
	v_cndmask_b32_e64 v110, 0, v110, s[18:19]
	v_pk_fma_f32 v[170:171], v[54:55], v[196:197], v[122:123]
	v_pk_fma_f32 v[154:155], v[50:51], v[180:181], v[154:155]
	v_pk_fma_f32 v[66:67], v[36:37], v[184:185], v[66:67]
	v_pk_fma_f32 v[54:55], v[54:55], v[194:195], v[122:123]
	v_pk_fma_f32 v[50:51], v[50:51], v[186:187], v[58:59]
	v_pk_fma_f32 v[36:37], v[36:37], v[44:45], v[48:49]
	v_lshlrev_b32_e32 v44, 16, v109
	v_and_b32_e32 v45, 0xffff0000, v109
	v_cndmask_b32_e64 v111, 0, v111, s[18:19]
	v_pk_fma_f32 v[170:171], v[46:47], v[194:195], v[170:171]
	v_pk_fma_f32 v[154:155], v[38:39], v[186:187], v[154:155]
	v_lshlrev_b32_e32 v196, 16, v107
	v_and_b32_e32 v197, 0xffff0000, v107
	v_pk_fma_f32 v[46:47], v[46:47], v[192:193], v[54:55]
	v_pk_fma_f32 v[38:39], v[38:39], v[44:45], v[50:51]
	v_lshlrev_b32_e32 v44, 16, v110
	v_and_b32_e32 v45, 0xffff0000, v110
	v_pk_fma_f32 v[170:171], v[42:43], v[192:193], v[170:171]
	v_pk_fma_f32 v[190:191], v[32:33], v[188:189], v[168:169]
	v_pk_fma_f32 v[42:43], v[42:43], v[196:197], v[46:47]
	v_pk_fma_f32 v[40:41], v[32:33], v[44:45], v[40:41]
	v_lshlrev_b32_e32 v32, 16, v111
	v_and_b32_e32 v33, 0xffff0000, v111
	v_pk_fma_f32 v[198:199], v[34:35], v[196:197], v[170:171]
	v_cvt_pk_bf16_f32 v168, v66, v67
	v_cvt_pk_bf16_f32 v169, v154, v155
	v_cvt_pk_bf16_f32 v170, v190, v191
	v_pk_fma_f32 v[42:43], v[34:35], v[32:33], v[42:43]
	v_cvt_pk_bf16_f32 v171, v198, v199
	ds_write_b128 v151, v[168:171] offset:1632
	v_cvt_pk_bf16_f32 v32, v36, v37
	v_cvt_pk_bf16_f32 v33, v38, v39
	v_cvt_pk_bf16_f32 v34, v40, v41
	v_cvt_pk_bf16_f32 v35, v42, v43
	s_cmp_eq_u32 s80, 0x80000
	ds_write_b128 v151, v[32:35] offset:1904
	s_cbranch_scc1 .LBB0_294
; __device__ __forceinline__ void lru_load_rows(u32x4 (&rows)[11], const LruTile& T, int tr, int cgp) {
;     const unsigned loff = (unsigned)(tr * 8 * T.ld + cgp * 8);
; #pragma unroll
;     for (int j = 0; j < 11; ++j) { const bf16_t* bj = T.src + (long)(T.t0 - 1 + j) * T.ld; rows[j] = *(const u32x4*)(bj + loff); }
; }
; template <int dir>
; __device__ __forceinline__ void lru_pass(LAS unsigned char* lds, const Params& P, int b, int h, int q, bool dry) {
;     ...
;             LruTile nxt = cur;
;             if (sc < 8) { nxt = lru_tile(Z, ZC, b, h, dir, sc + 1); lru_load_rows(rows, nxt, tr, cgp);
; #pragma unroll
;                 for (int i = 0; i < NIN; ++i) { const int id = tid + i * NTHREADS;
;                     if (dir == 0) inr[i] = *(const u32x4*)(Zg + (size_t)(nxt.t0 + (id >> 2)) * 128 + (id & 3) * 8);
;                     else inr[i] = *(const u32x4*)(Hg + (size_t)(nxt.t0 + (id >> 3)) * DM + (id & 7) * 4); } }
	v_lshl_add_u64 v[32:33], v[136:137], 0, s[80:81]
	global_load_dwordx4 v[68:71], v[32:33], off offset:-1280
	global_load_dwordx4 v[72:75], v[32:33], off offset:-1024
	global_load_dwordx4 v[76:79], v[32:33], off offset:-768
	global_load_dwordx4 v[80:83], v[32:33], off offset:-512
	global_load_dwordx4 v[84:87], v[32:33], off offset:-256
	global_load_dwordx4 v[88:91], v[32:33], off
	global_load_dwordx4 v[92:95], v[32:33], off offset:256
	global_load_dwordx4 v[96:99], v[32:33], off offset:512
	global_load_dwordx4 v[100:103], v[32:33], off offset:768
	global_load_dwordx4 v[104:107], v[32:33], off offset:1024
	global_load_dwordx4 v[108:111], v[32:33], off offset:1280
	s_movk_i32 s92, 0x800
	s_mov_b32 s20, s90
	s_branch .LBB0_295

; #define LAS __attribute__((address_space(3)))
; __device__ __forceinline__ unsigned cvt_pk_bf16(float lo, float hi) { unsigned r; asm volatile("v_cvt_pk_bf16_f32 %0, %1, %2" : "=v"(r) : "v"(lo), "v"(hi)); return r; }
; __device__ __forceinline__ float bf_lo(unsigned u) { return __uint_as_float(u << 16); }
; __device__ __forceinline__ float bf_hi(unsigned u) { return __uint_as_float(u & 0xffff0000u); }
; __device__ __forceinline__ bf16_t f2bf(float f) { return (bf16_t)(cvt_pk_bf16(f, 0.f) & 0xffffu); }
; #define LDS_BARRIER() do { asm volatile("s_waitcnt lgkmcnt(0)" ::: "memory"); __builtin_amdgcn_s_barrier(); asm volatile("" ::: "memory"); } while (0)
; template <int dir>
; __device__ __forceinline__ void lru_pass(LAS unsigned char* lds, const Params& P, int b, int h, int q, bool dry) {
;     ...
;             const float Po = __shfl_xor(Pp, 32), Eo = __shfl_xor(E, 32);
;             const float P0 = g ? Po : Pp, E0 = g ? Eo : E, P1 = g ? Pp : Po, E1 = g ? E : Eo;
;             if (g == 0) { AGG[(wid * 2 + 0) * 32 + nl] = P0 * P1; AGG[(wid * 2 + 1) * 32 + nl] = fmaf(P1, E0, E1); }
;             LDS_BARRIER();
;             float cin = carry, cend = carry;
; #pragma unroll
;             for (int w = 0; w < 8; ++w) { const float pw = AGG[(w * 2 + 0) * 32 + nl], ew = AGG[(w * 2 + 1) * 32 + nl]; if (w == wid) cin = cend; cend = fmaf(pw, cend, ew); }
;             carry = cend;
;             if (g) cin = fmaf(P0, cin, E0);
;             if (!isctx) {
; #pragma unroll
;                 for (int v = 0; v < 16; ++v) { const float hv = fmaf(zi[v], cin, zr[v]);
;                     const int s = sbase + v; const int tl = dir == 0 ? s : 255 - s;
;                     if (dir == 0) *(LAS unsigned*)(TOUT + tl * IO_WP + nl * 4) = (cvt_pk_bf16(hv, 0.f) & 0xffffu) | (pk[v] << 16);
;                     else *(LAS bf16_t*)(TOUT + tl * IO_NP + nl * 2) = f2bf((bf_lo(pk[v]) + hv) * bf_hi(pk[v])); }
.LBB0_299:
	s_or_b64 exec, exec, s[18:19]
	s_waitcnt lgkmcnt(0)
	s_barrier
	s_setprio 1
	v_add_u32_e32 v34, s99, v140
	ds_read2_b32 v[36:37], v34 offset1:32
	ds_read2_b32 v[38:39], v34 offset0:64 offset1:96
	ds_read2_b32 v[40:41], v34 offset0:128 offset1:160
	ds_read2_b32 v[42:43], v34 offset0:192 offset1:224
	v_add_u32_e32 v32, s100, v140
	ds_read2_b32 v[44:45], v32 offset1:32
	s_waitcnt lgkmcnt(4)
	v_fmac_f32_e32 v37, v36, v165
	ds_read2_b32 v[46:47], v32 offset0:64 offset1:96
	s_waitcnt lgkmcnt(4)
	v_fmac_f32_e32 v39, v38, v37
	ds_read2_b32 v[34:35], v32 offset0:128 offset1:160
	s_waitcnt lgkmcnt(4)
	v_fmac_f32_e32 v41, v40, v39
	ds_read2_b32 v[32:33], v32 offset0:192 offset1:224
	s_waitcnt lgkmcnt(4)
	v_fmac_f32_e32 v43, v42, v41
	s_waitcnt lgkmcnt(3)
	v_fmac_f32_e32 v45, v44, v43
	s_waitcnt lgkmcnt(2)
	v_fmac_f32_e32 v47, v46, v45
	s_cmp_eq_u32 s80, 0
	s_waitcnt lgkmcnt(1)
	v_fmac_f32_e32 v35, v34, v47
	s_cbranch_scc1 .LBB0_301
	v_cndmask_b32_e64 v37, v165, v37, s[14:15]
	v_cndmask_b32_e64 v37, v37, v39, s[12:13]
	v_cndmask_b32_e64 v37, v37, v41, s[10:11]
	v_cndmask_b32_e64 v37, v37, v43, s[8:9]
	v_cndmask_b32_e64 v37, v37, v45, s[4:5]
	v_cndmask_b32_e64 v37, v37, v47, s[16:17]
	v_cndmask_b32_e64 v37, v37, v35, s[0:1]
	v_fmac_f32_e32 v189, v188, v37
	v_cndmask_b32_e32 v34, v189, v37, vcc
	v_fmac_f32_e32 v49, v171, v34
	v_fmac_f32_e32 v172, v50, v34
	v_fmac_f32_e32 v173, v51, v34
	v_fmac_f32_e32 v174, v52, v34
	v_fmac_f32_e32 v175, v53, v34
	v_fmac_f32_e32 v176, v54, v34
	v_fmac_f32_e32 v177, v55, v34
	v_fmac_f32_e32 v178, v56, v34
	v_fmac_f32_e32 v179, v57, v34
	v_fmac_f32_e32 v180, v58, v34
	v_fmac_f32_e32 v181, v59, v34
	v_fmac_f32_e32 v182, v60, v34
	v_fmac_f32_e32 v183, v61, v34
	v_fmac_f32_e32 v184, v62, v34
	v_fmac_f32_e32 v63, v186, v34
	v_fmac_f32_e32 v185, v187, v34
	v_cvt_pk_bf16_f32 v36, v49, v172
	ds_write_b16 v164, v36
	ds_write_b16_d16_hi v164, v36 offset:80
	v_cvt_pk_bf16_f32 v37, v173, v174
	ds_write_b16 v164, v37 offset:160
	ds_write_b16_d16_hi v164, v37 offset:240
	v_cvt_pk_bf16_f32 v38, v175, v176
	ds_write_b16 v164, v38 offset:320
	ds_write_b16_d16_hi v164, v38 offset:400
	v_cvt_pk_bf16_f32 v39, v177, v178
	ds_write_b16 v164, v39 offset:480
	ds_write_b16_d16_hi v164, v39 offset:560
	v_cvt_pk_bf16_f32 v36, v179, v180
	ds_write_b16 v164, v36 offset:640
	ds_write_b16_d16_hi v164, v36 offset:720
	v_cvt_pk_bf16_f32 v37, v181, v182
	ds_write_b16 v164, v37 offset:800
	ds_write_b16_d16_hi v164, v37 offset:880
	v_cvt_pk_bf16_f32 v38, v183, v184
	ds_write_b16 v164, v38 offset:960
	ds_write_b16_d16_hi v164, v38 offset:1040
	v_cvt_pk_bf16_f32 v39, v63, v185
	ds_write_b16 v164, v39 offset:1120
	ds_write_b16_d16_hi v164, v39 offset:1200

; #define LAS __attribute__((address_space(3)))
; #define LDS_BARRIER() do { asm volatile("s_waitcnt lgkmcnt(0)" ::: "memory"); __builtin_amdgcn_s_barrier(); asm volatile("" ::: "memory"); } while (0)
; template <int dir>
; __device__ __forceinline__ void lru_pass(LAS unsigned char* lds, const Params& P, int b, int h, int q, bool dry) {
;     ...
;     {
; #pragma unroll
;         for (int i = 0; i < 2; ++i) { const int idx = tid + i * NTHREADS, gate = idx >> 9, n = (idx >> 4) & 31, kc = idx & 15;
;             *(LAS u32x4*)(WB + (gate * 32 + n) * XC_PITCH + kc * 16) = *(const u32x4*)(LruW + ((size_t)((dir * 2 + gate) * 8 + h) * 128 + q * 32 + n) * 128 + kc * 8); }
;         const float br = -LOG2E * P.lru_ba[(dir * 8 + h) * 128 + chl], bi = -LOG2E * P.lru_bx[(dir * 8 + h) * 128 + chl];
;         const float lam = P.lru_lambda[dir * 1024 + ch];
;         const float cl = -8.0f * LOG2E * log1pf(__expf(-lam));
;     ...
;         LDS_BARRIER();
;         if (dir == 0) {
; #pragma unroll
;             for (int i = 0; i < 4; ++i) { const int id = tid + i * NTHREADS; *(u32x4*)(Hg + (size_t)(t0_prev + (id >> 3)) * DM + (id & 7) * 4) = *(const LAS u32x4*)(TOUT + (id >> 3) * IO_WP + (id & 7) * 16); }
;         } else if (!dry) {
; #pragma unroll
;             for (int i = 0; i < 2; ++i) { const int id = tid + i * NTHREADS; *(u32x4*)(Z + ZSLAB(8 + h, (size_t)b * SEQ + t0_prev + (id >> 2)) + q * 32 + (id & 3) * 8) = *(const LAS u32x4*)(TOUT + (id >> 2) * IO_NP + (id & 3) * 16); }
;         }
.Lpp_f_noy:
	s_waitcnt lgkmcnt(0)
	s_barrier
	s_add_u32 s18, s80, 0x5fe0000
	s_addc_u32 s19, s81, 0
	ds_read_b128 v[0:3], v158
	ds_read_b128 v[4:7], v159
	v_lshl_add_u64 v[8:9], v[134:135], 0, s[18:19]
	v_lshl_add_u64 v[10:11], v[132:133], 0, s[18:19]
	s_waitcnt lgkmcnt(1)
	global_store_dwordx4 v[8:9], v[0:3], off
	s_waitcnt lgkmcnt(0)
	global_store_dwordx4 v[10:11], v[4:7], off
	s_waitcnt lgkmcnt(0)
	s_add_u32 s42, s22, 0x1b00000
	s_addc_u32 s43, s23, 0
	v_mov_b32_e32 v32, v167
	s_barrier
	s_or_b32 s0, s26, 16
	v_and_b32_e32 v15, 31, v32
	v_or_b32_e32 v17, s28, v15
	v_add_u32_e32 v13, 0x200, v32
	v_or_b32_e32 v8, s27, v17
	v_ashrrev_i32_e32 v11, 9, v32
	v_ashrrev_i32_e32 v14, 9, v13
	v_lshlrev_b32_e32 v8, 2, v8
	v_mov_b32_e32 v9, v65
	v_lshl_add_u32 v2, v11, 3, s0
	v_lshl_add_u32 v6, v14, 3, s0
	v_lshl_add_u64 v[8:9], s[64:65], 0, v[8:9]
	s_movk_i32 s0, 0x1000
	v_add_co_u32_e32 v8, vcc, s0, v8
	v_and_b32_e32 v12, 15, v32
	s_nop 0
	v_addc_co_u32_e32 v9, vcc, 0, v9, vcc
	global_load_dword v16, v[8:9], off
	v_bfe_u32 v10, v32, 4, 5
	v_lshlrev_b32_e32 v64, 4, v12
	v_ashrrev_i32_e32 v3, 31, v2
	v_ashrrev_i32_e32 v7, 31, v6
	v_or_b32_e32 v4, s28, v10
	v_lshl_add_u64 v[0:1], s[38:39], 0, v[64:65]
	v_lshlrev_b64 v[2:3], 15, v[2:3]
	v_lshlrev_b64 v[6:7], 15, v[6:7]
	v_lshlrev_b32_e32 v4, 8, v4
	v_mov_b32_e32 v5, v65
	v_lshl_add_u64 v[2:3], v[0:1], 0, v[2:3]
	v_lshl_add_u64 v[0:1], v[0:1], 0, v[6:7]
	v_lshl_add_u64 v[2:3], v[2:3], 0, v[4:5]
	v_lshl_add_u64 v[4:5], v[0:1], 0, v[4:5]
	global_load_dwordx4 v[0:3], v[2:3], off
	s_nop 0
	global_load_dwordx4 v[4:7], v[4:5], off
	v_lshrrev_b32_e32 v8, 1, v32
	v_lshlrev_b32_e32 v9, 2, v32
	v_and_b32_e32 v20, 12, v8
	v_lshl_or_b32 v11, v11, 5, v10
	v_add_u32_e32 v8, s88, v64
	v_lshl_or_b32 v14, v14, 5, v10
	v_mad_u64_u32 v[10:11], s[6:7], v11, s89, v[8:9]
	s_or_b32 s8, s26, 8
	v_and_or_b32 v20, v9, 16, v20
	v_lshlrev_b32_e32 v21, 2, v17
	v_mad_u64_u32 v[8:9], s[6:7], v14, s89, v[8:9]
	v_lshl_or_b32 v9, s8, 9, v21
	global_load_dword v14, v9, s[58:59]
	s_nop 0
	global_load_dword v9, v9, s[62:63]
	s_mov_b32 s80, 0x3f2aaaab
	s_mov_b32 s81, 0x3f317218
	s_mov_b32 s91, 0x7f800000
	s_mov_b32 s92, 0x33800000
	v_ashrrev_i32_e32 v33, 4, v32
	v_lshlrev_b32_e32 v34, 3, v12
	v_readfirstlane_b32 s4, v32
	s_lshl_b64 s[0:1], s[78:79], 11
	s_lshl_b32 s5, s8, 14
	s_ashr_i32 s6, s4, 6
	s_add_u32 s26, s0, s5
	s_addc_u32 s27, s1, 0
	s_lshl_b32 s0, s28, 1
	v_readlane_b32 s1, v255, 10
	v_and_b32_e32 v19, 3, v32
	s_add_u32 s0, s1, s0
	v_bfe_u32 v18, v32, 5, 1
	v_add_u32_e32 v44, 0, v64
	v_lshlrev_b32_e32 v64, 4, v19
	s_addc_u32 s1, s3, 0
	v_lshl_add_u64 v[136:137], s[0:1], 0, v[64:65]
	s_lshl_b32 s0, s6, 5
	v_lshlrev_b32_e32 v46, 4, v18
	v_or_b32_e32 v37, s0, v46
	v_add_u32_e32 v158, s86, v64
	v_or_b32_e32 v64, 4, v37
	s_movk_i32 s93, 0x880
	v_ashrrev_i32_e32 v36, 3, v32
	v_ashrrev_i32_e32 v38, 3, v13
	v_ashrrev_i32_e32 v140, 2, v32
	v_sub_u32_e32 v39, 0xff, v37
	v_sub_u32_e32 v64, 0xff, v64
	v_lshl_add_u32 v160, v33, 3, -1
	v_mul_lo_u32 v52, v33, s93
	v_lshl_or_b32 v110, v33, 13, v34
	v_mov_b32_e32 v111, v65
	v_lshlrev_b64 v[110:111], 1, v[110:111]
	v_lshl_add_u64 v[108:109], s[48:49], 0, v[110:111]
	global_load_dwordx4 v[68:71], v[108:109], off offset:-2048
	global_load_dwordx4 v[72:75], v[108:109], off
	global_load_dwordx4 v[76:79], v[108:109], off offset:2048
	v_lshl_add_u64 v[108:109], s[50:51], 0, v[110:111]
	global_load_dwordx4 v[80:83], v[108:109], off
	v_lshl_add_u64 v[108:109], s[56:57], 0, v[110:111]
	global_load_dwordx4 v[84:87], v[108:109], off
	v_lshl_add_u64 v[108:109], s[60:61], 0, v[110:111]
	global_load_dwordx4 v[88:91], v[108:109], off
	v_lshl_add_u64 v[108:109], s[66:67], 0, v[110:111]
	global_load_dwordx4 v[92:95], v[108:109], off
	v_lshl_add_u64 v[108:109], s[70:71], 0, v[110:111]
	global_load_dwordx4 v[96:99], v[108:109], off
	v_lshl_add_u64 v[108:109], s[72:73], 0, v[110:111]
	global_load_dwordx4 v[100:103], v[108:109], off
	v_lshl_add_u64 v[108:109], s[74:75], 0, v[110:111]
	global_load_dwordx4 v[104:107], v[108:109], off
	v_lshl_add_u64 v[108:109], s[76:77], 0, v[110:111]
	global_load_dwordx4 v[108:111], v[108:109], off
	s_waitcnt vmcnt(14)
	ds_write_b128 v10, v[0:3]
	s_waitcnt vmcnt(13)
	ds_write_b128 v8, v[4:7]
	v_mul_f32_e32 v11, 0xbfb8aa3b, v16
	v_exp_f32_e32 v11, v11
	v_mul_lo_u32 v57, v39, s89
	v_mul_lo_u32 v58, v39, s30
	v_mul_lo_u32 v114, v64, s89
	v_add_f32_e32 v2, 1.0, v11
	v_add_f32_e32 v3, -1.0, v2
	v_frexp_mant_f32_e32 v4, v2
	v_cvt_f64_f32_e32 v[0:1], v2
	v_sub_f32_e32 v5, v3, v2
	v_frexp_exp_i32_f64_e32 v0, v[0:1]
	v_cmp_gt_f32_e32 vcc, s80, v4
	v_sub_f32_e32 v3, v11, v3
	v_add_f32_e32 v1, 1.0, v5
	v_subbrev_co_u32_e32 v0, vcc, 0, v0, vcc
	v_add_f32_e32 v1, v3, v1
	v_sub_u32_e32 v3, 0, v0
	v_ldexp_f32 v2, v2, v3
	v_ldexp_f32 v1, v1, v3
	v_add_f32_e32 v3, -1.0, v2
	v_add_f32_e32 v4, 1.0, v2
	v_add_f32_e32 v5, 1.0, v3
	v_add_f32_e32 v6, -1.0, v4
	v_sub_f32_e32 v5, v2, v5
	v_sub_f32_e32 v2, v2, v6
	v_add_f32_e32 v5, v1, v5
	v_add_f32_e32 v1, v1, v2
	v_add_f32_e32 v7, v4, v1
	v_rcp_f32_e32 v8, v7
	v_add_f32_e32 v2, v3, v5
	v_sub_f32_e32 v4, v7, v4
	v_sub_f32_e32 v3, v2, v3
	v_sub_f32_e32 v1, v1, v4
	v_mul_f32_e32 v4, v2, v8
	v_sub_f32_e32 v3, v5, v3
	v_mul_f32_e32 v5, v7, v4
	v_fma_f32 v10, v4, v7, -v5
	v_fmac_f32_e32 v10, v4, v1
	v_add_f32_e32 v16, v5, v10
	v_sub_f32_e32 v21, v2, v16
	v_sub_f32_e32 v2, v2, v21
	v_sub_f32_e32 v5, v16, v5
	v_sub_f32_e32 v2, v2, v16
	v_sub_f32_e32 v5, v5, v10
	v_add_f32_e32 v2, v3, v2
	v_add_f32_e32 v2, v5, v2
	v_add_f32_e32 v3, v21, v2
	v_mul_f32_e32 v5, v8, v3
	v_sub_f32_e32 v10, v21, v3
	v_mul_f32_e32 v16, v7, v5
	v_add_f32_e32 v2, v2, v10
	v_add_f32_e32 v10, v4, v5
; template <int dir>
; __device__ __forceinline__ void lru_pass(LAS unsigned char* lds, const Params& P, int b, int h, int q, bool dry) {
;     ...
;         const float br = -LOG2E * P.lru_ba[(dir * 8 + h) * 128 + chl], bi = -LOG2E * P.lru_bx[(dir * 8 + h) * 128 + chl];
;         const float lam = P.lru_lambda[dir * 1024 + ch];
;         const float cl = -8.0f * LOG2E * log1pf(__expf(-lam));
;     ...
;             unsigned xcb[16], pk[16];
; #pragma unroll
;             for (int v = 0; v < 16; ++v) { const int s = sbase + v; const int tl = dir == 0 ? s : 255 - s; xcb[v] = *(const LAS bf16_t*)(XC + tl * XC_PITCH + chl * 2);
;                 if (dir == 0) pk[v] = *(const LAS bf16_t*)(TIN + tl * IO_NP + nl * 2); else pk[v] = *(const LAS unsigned*)(TIN + tl * IO_WP + nl * 4); }
;             float Pp = 1.f, E = 0.f;
; #pragma unroll
;             for (int v = 0; v < 16; ++v) {
;                 const float xcv = __uint_as_float(xcb[v] << 16);
;                 const float r = __builtin_amdgcn_rcpf(1.0f + __builtin_amdgcn_exp2f(zr[v]));
;                 const float ig = __builtin_amdgcn_rcpf(1.0f + __builtin_amdgcn_exp2f(zi[v]));
;                 const float a = __builtin_amdgcn_exp2f(cl * r);
;                 const float sq = __builtin_amdgcn_sqrtf(fmaf(-a, a, 1.0f));
;                 const float u = sq * ig * xcv;
;                 E = fmaf(a, E, u); Pp *= a; zr[v] = E; zi[v] = Pp; }
;             const float Po = __shfl_xor(Pp, 32), Eo = __shfl_xor(E, 32);
;             const float P0 = g ? Po : Pp, E0 = g ? Eo : E, P1 = g ? Pp : Po, E1 = g ? E : Eo;
;             if (g == 0) { AGG[(wid * 2 + 0) * 32 + nl] = P0 * P1; AGG[(wid * 2 + 1) * 32 + nl] = fmaf(P1, E0, E1); }
;             LDS_BARRIER();
;             float cin = carry, cend = carry;
; #pragma unroll
;             for (int w = 0; w < 8; ++w) { const float pw = AGG[(w * 2 + 0) * 32 + nl], ew = AGG[(w * 2 + 1) * 32 + nl]; if (w == wid) cin = cend; cend = fmaf(pw, cend, ew); }
;             carry = cend;
;             if (g) cin = fmaf(P0, cin, E0);
;             if (!isctx) {
; #pragma unroll
;                 for (int v = 0; v < 16; ++v) { const float hv = fmaf(zi[v], cin, zr[v]);
;                     const int s = sbase + v; const int tl = dir == 0 ? s : 255 - s;
;                     if (dir == 0) *(LAS unsigned*)(TOUT + tl * IO_WP + nl * 4) = (cvt_pk_bf16(hv, 0.f) & 0xffffu) | (pk[v] << 16);
	v_fma_f32 v7, v5, v7, -v16
	v_sub_f32_e32 v4, v10, v4
	v_fmac_f32_e32 v7, v5, v1
	v_sub_f32_e32 v1, v5, v4
	v_add_f32_e32 v4, v16, v7
	v_sub_f32_e32 v5, v4, v16
	v_sub_f32_e32 v16, v3, v4
	v_sub_f32_e32 v3, v3, v16
	v_sub_f32_e32 v3, v3, v4
	v_cvt_f32_i32_e32 v0, v0
	v_sub_f32_e32 v5, v5, v7
	v_add_f32_e32 v2, v2, v3
	v_add_f32_e32 v2, v5, v2
	v_add_f32_e32 v2, v16, v2
	v_mul_f32_e32 v2, v8, v2
	v_mul_f32_e32 v6, 0x3f317218, v0
	v_add_f32_e32 v1, v1, v2
	v_add_f32_e32 v2, v10, v1
	v_fma_f32 v5, v0, s81, -v6
	v_fmac_f32_e32 v5, 0xb102e308, v0
	v_sub_f32_e32 v0, v2, v10
	v_mul_f32_e32 v3, v2, v2
	v_sub_f32_e32 v0, v1, v0
	v_add_f32_e32 v1, v6, v5
	v_fmamk_f32 v4, v3, 0x3e9b6dac, v200
	v_sub_f32_e32 v6, v1, v6
	v_fmaak_f32 v4, v3, v4, 0x3f2aaada
	v_sub_f32_e32 v5, v5, v6
	v_ldexp_f32 v6, v2, 1
	v_mul_f32_e32 v2, v2, v3
	v_mul_f32_e32 v2, v2, v4
	v_add_f32_e32 v3, v6, v2
	v_sub_f32_e32 v4, v3, v6
	v_ldexp_f32 v0, v0, 1
	v_sub_f32_e32 v2, v2, v4
	v_add_f32_e32 v0, v0, v2
	v_add_f32_e32 v2, v3, v0
	v_sub_f32_e32 v3, v2, v3
	v_sub_f32_e32 v0, v0, v3
	v_add_f32_e32 v3, v1, v2
	v_sub_f32_e32 v4, v3, v1
	v_sub_f32_e32 v6, v3, v4
	v_sub_f32_e32 v1, v1, v6
	v_sub_f32_e32 v2, v2, v4
	v_add_f32_e32 v1, v2, v1
	v_add_f32_e32 v2, v5, v0
	v_sub_f32_e32 v4, v2, v5
	v_add_f32_e32 v1, v2, v1
	v_sub_f32_e32 v6, v2, v4
	v_add_f32_e32 v2, v3, v1
	v_sub_f32_e32 v5, v5, v6
	v_sub_f32_e32 v0, v0, v4
	v_sub_f32_e32 v3, v2, v3
	v_add_f32_e32 v0, v0, v5
	v_sub_f32_e32 v1, v1, v3
	v_add_f32_e32 v0, v0, v1
	v_add_f32_e32 v0, v2, v0
	v_cmp_neq_f32_e32 vcc, s91, v11
	v_mov_b32_e32 v1, v65
	v_mul_lo_u32 v115, v64, s30
	v_cndmask_b32_e32 v0, v201, v0, vcc
	v_cmp_ngt_f32_e32 vcc, -1.0, v11
	v_mul_lo_u32 v206, v39, s87
	v_mul_lo_u32 v210, v64, s87
	v_cndmask_b32_e32 v0, v202, v0, vcc
	v_cmp_neq_f32_e32 vcc, -1.0, v11
	v_ashrrev_i32_e32 v39, 31, v38
	v_sub_u32_e32 v41, 0xfe, v37
	v_cndmask_b32_e32 v0, v203, v0, vcc
	v_cmp_lt_f32_e64 vcc, |v11|, s92
	v_mul_lo_u32 v59, v41, s89
	v_mul_lo_u32 v60, v41, s30
	v_cndmask_b32_e32 v6, v0, v11, vcc
	v_lshlrev_b32_e32 v2, 4, v32
	v_and_b32_e32 v2, 0x70, v2
	v_lshlrev_b32_e32 v1, 2, v15
	v_add_u32_e32 v45, s95, v2
	v_or3_b32 v2, v19, v20, s0
	s_and_b32 s0, s4, 0x3fffffc0
	v_add_u32_e32 v161, s94, v1
	s_cmp_eq_u32 s6, 7
	v_lshl_add_u32 v254, s0, 2, v161
	s_cselect_b64 s[0:1], -1, 0
	s_cmp_eq_u32 s6, 6
	s_cselect_b64 s[16:17], -1, 0
	s_cmp_eq_u32 s6, 5
	s_cselect_b64 s[4:5], -1, 0
	s_cmp_eq_u32 s6, 4
	s_cselect_b64 s[8:9], -1, 0
	s_cmp_eq_u32 s6, 3
	s_cselect_b64 s[10:11], -1, 0
	s_cmp_eq_u32 s6, 2
	s_cselect_b64 s[12:13], -1, 0
	s_cmp_eq_u32 s6, 1
	s_cselect_b64 s[14:15], -1, 0
	s_lshl_b32 s6, s25, 7
	s_and_b32 s6, s6, 0xe00
	s_lshl_b32 s7, s29, 7
	s_or_b32 s6, s7, s6
	s_add_u32 s6, s6, s44
	v_add_u32_e32 v50, s95, v1
	v_add_u32_e32 v1, 0x400, v32
	s_addc_u32 s7, 0, s45
	v_ashrrev_i32_e32 v40, 3, v1
	v_add_u32_e32 v1, 0x600, v32
	v_and_b32_e32 v32, 7, v32
	s_add_u32 s18, s84, s46
	v_lshlrev_b32_e32 v64, 4, v32
	v_lshl_or_b32 v32, v33, 10, v34
	v_mov_b32_e32 v33, v65
	s_addc_u32 s19, s85, s47
	v_lshl_add_u64 v[144:145], v[32:33], 1, s[18:19]
	v_lshlrev_b64 v[32:33], 12, v[38:39]
	v_lshl_add_u64 v[32:33], s[6:7], 0, v[32:33]
	v_mul_lo_u32 v207, v41, s87
	v_lshl_add_u64 v[32:33], v[32:33], 0, v[64:65]
	v_ashrrev_i32_e32 v41, 31, v40
	v_or_b32_e32 v43, 2, v37
	v_lshl_add_u64 v[252:253], s[42:43], 0, v[32:33]
	v_lshlrev_b64 v[32:33], 12, v[40:41]
	v_ashrrev_i32_e32 v42, 3, v1
	v_sub_u32_e32 v43, 0xff, v43
	v_or_b32_e32 v63, 3, v37
	v_or_b32_e32 v66, 5, v37
	v_or_b32_e32 v67, 6, v37
	v_or_b32_e32 v120, 7, v37
	v_or_b32_e32 v123, 8, v37
	v_or_b32_e32 v126, 9, v37
	v_or_b32_e32 v129, 10, v37
	v_or_b32_e32 v132, 11, v37
	v_or_b32_e32 v135, 12, v37
	v_or_b32_e32 v142, 13, v37
	v_or_b32_e32 v143, 14, v37
	v_or_b32_e32 v37, 15, v37
	v_lshl_add_u64 v[32:33], s[6:7], 0, v[32:33]
	v_mul_lo_u32 v61, v43, s89
	v_mul_lo_u32 v62, v43, s30
	v_sub_u32_e32 v37, 0xff, v37
	v_mul_lo_u32 v208, v43, s87
	v_lshl_add_u64 v[32:33], v[32:33], 0, v[64:65]
	v_ashrrev_i32_e32 v43, 31, v42
	v_sub_u32_e32 v2, 0xff, v2
	v_mul_lo_u32 v204, v37, s89
	v_mul_lo_u32 v205, v37, s30
	v_mul_lo_u32 v221, v37, s87
	v_ashrrev_i32_e32 v37, 31, v36
	v_lshl_add_u64 v[154:155], s[42:43], 0, v[32:33]
	v_lshlrev_b64 v[32:33], 12, v[42:43]
	v_mul_lo_u32 v2, v2, s89
	v_mul_lo_u32 v53, v36, s30
	v_sub_u32_e32 v63, 0xff, v63
	v_sub_u32_e32 v66, 0xff, v66
	v_sub_u32_e32 v67, 0xff, v67
	v_sub_u32_e32 v120, 0xff, v120
	v_sub_u32_e32 v123, 0xff, v123
	v_sub_u32_e32 v126, 0xff, v126
	v_lshlrev_b64 v[36:37], 12, v[36:37]
	v_lshl_add_u64 v[32:33], s[6:7], 0, v[32:33]
	v_lshlrev_b32_e32 v35, 4, v12
	v_add_u32_e32 v47, 0, v2
	v_mov_b32_e32 v2, s88
	v_lshl_add_u32 v49, v17, 1, 0
	v_lshl_add_u32 v51, v15, 1, s86
	v_mul_lo_u32 v112, v63, s89
	v_mul_lo_u32 v113, v63, s30
	v_mul_lo_u32 v116, v66, s89
	v_mul_lo_u32 v117, v66, s30
	v_mul_lo_u32 v118, v67, s89
	v_mul_lo_u32 v119, v67, s30
	v_mul_lo_u32 v121, v120, s89
	v_mul_lo_u32 v122, v120, s30
	v_mul_lo_u32 v124, v123, s89
	v_mul_lo_u32 v125, v123, s30
	v_mul_lo_u32 v127, v126, s89
	v_mul_lo_u32 v128, v126, s30
	v_sub_u32_e32 v129, 0xff, v129
	v_sub_u32_e32 v132, 0xff, v132
	v_sub_u32_e32 v135, 0xff, v135
	v_sub_u32_e32 v142, 0xff, v142
	v_sub_u32_e32 v143, 0xff, v143
	v_mul_lo_u32 v211, v66, s87
	v_mul_lo_u32 v212, v67, s87
	v_mul_lo_u32 v120, v120, s87
	v_mul_lo_u32 v123, v123, s87
	v_mul_lo_u32 v126, v126, s87
	v_lshl_add_u64 v[36:37], s[6:7], 0, v[36:37]
	v_lshl_add_u64 v[32:33], v[32:33], 0, v[64:65]
	v_mov_b32_e32 v66, v65
	v_mov_b32_e32 v67, v65
	s_waitcnt vmcnt(12)
	v_mul_f32_e32 v0, 0xbfb8aa3b, v14
	s_waitcnt vmcnt(11)
; #define LAS __attribute__((address_space(3)))
; template <int dir>
; __device__ __forceinline__ void lru_pass(LAS unsigned char* lds, const Params& P, int b, int h, int q, bool dry) {
;     ...
;         const float cl = -8.0f * LOG2E * log1pf(__expf(-lam));
;     ...
;             f32x16 zr, zi;
; #pragma unroll
;             for (int v = 0; v < 16; ++v) { zr[v] = br; zi[v] = bi; }
;             const int sbase = 32 * wid + 16 * g;
;             { const int sl = 32 * wid + s_i; const int tlA = dir == 0 ? sl : 255 - sl;
;               const LAS unsigned char* ap = XC + tlA * XC_PITCH + 16 * g;
;               const LAS unsigned char* wrp = WB + nl * XC_PITCH + 16 * g; const LAS unsigned char* wip = wrp + 32 * XC_PITCH;
; #pragma unroll
;               for (int ks = 0; ks < 8; ++ks) { const bf16x8 A = *(const LAS bf16x8*)(ap + 32 * ks);
;                   const bf16x8 Br = *(const LAS bf16x8*)(wrp + 32 * ks), Bi = *(const LAS bf16x8*)(wip + 32 * ks);
;                   zr = __builtin_amdgcn_mfma_f32_32x32x16_bf16(A, Br, zr, 0, 0, 0); zi = __builtin_amdgcn_mfma_f32_32x32x16_bf16(A, Bi, zi, 0, 0, 0); } }
;             unsigned xcb[16], pk[16];
; #pragma unroll
;             for (int v = 0; v < 16; ++v) { const int s = sbase + v; const int tl = dir == 0 ? s : 255 - s; xcb[v] = *(const LAS bf16_t*)(XC + tl * XC_PITCH + chl * 2);
;                 if (dir == 0) pk[v] = *(const LAS bf16_t*)(TIN + tl * IO_NP + nl * 2); else pk[v] = *(const LAS unsigned*)(TIN + tl * IO_WP + nl * 4); }
	v_mul_f32_e32 v16, 0xbfb8aa3b, v9
	v_mad_u32_u24 v48, v15, s89, v2
	v_mul_lo_u32 v54, v38, s30
	v_mul_lo_u32 v55, v40, s30
	v_mul_lo_u32 v56, v42, s30
	v_ashrrev_i32_e32 v138, 2, v13
	v_mul_lo_u32 v130, v129, s89
	v_mul_lo_u32 v131, v129, s30
	v_mul_lo_u32 v133, v132, s89
	v_mul_lo_u32 v134, v132, s30
	v_mul_lo_u32 v146, v135, s89
	v_mul_lo_u32 v147, v135, s30
	v_mul_lo_u32 v148, v142, s89
	v_mul_lo_u32 v149, v142, s30
	v_mul_lo_u32 v162, v143, s89
	v_mul_lo_u32 v163, v143, s30
	v_mul_lo_u32 v63, v63, s87
	v_mul_lo_u32 v129, v129, s87
	v_mul_lo_u32 v132, v132, s87
	v_mul_lo_u32 v135, v135, s87
	v_mul_lo_u32 v219, v142, s87
	v_mul_lo_u32 v220, v143, s87
	v_lshl_add_u64 v[36:37], v[36:37], 0, v[64:65]
	v_lshl_add_u64 v[150:151], s[42:43], 0, v[32:33]
	v_mov_b32_e32 v64, v65
	v_add_u32_e32 v32, 0, v35
	v_add_u32_e32 v180, v49, v112
	v_add_u32_e32 v181, v50, v113
	v_add_u32_e32 v182, v49, v114
	v_add_u32_e32 v183, v50, v115
	v_add_u32_e32 v184, v49, v116
	v_add_u32_e32 v185, v50, v117
	v_add_u32_e32 v186, v49, v118
	v_add_u32_e32 v187, v50, v119
	v_add_u32_e32 v188, v49, v121
	v_add_u32_e32 v189, v50, v122
	v_add_u32_e32 v190, v49, v124
	v_add_u32_e32 v191, v50, v125
	v_add_u32_e32 v192, v49, v127
	v_add_u32_e32 v213, v51, v120
	v_add_u32_e32 v214, v51, v123
	v_add_u32_e32 v215, v51, v126
	v_mov_b64_e32 v[114:115], v[66:67]
	v_mov_b64_e32 v[118:119], v[66:67]
	v_mov_b64_e32 v[122:123], v[66:67]
	v_mov_b64_e32 v[126:127], v[66:67]
	s_mov_b32 s78, 0
	v_mov_b32_e32 v156, 0xff800000
	v_mul_f32_e32 v159, 0xc138aa3b, v6
	v_rcp_f32_e32 v159, v159
	s_nop 0
	v_cmp_eq_u32_e32 vcc, 0, v18
	v_mul_lo_u32 v164, v140, s87
	v_ashrrev_i32_e32 v141, 31, v140
	v_mul_lo_u32 v152, v138, s87
	v_ashrrev_i32_e32 v139, 31, v138
	v_mov_b32_e32 v1, v0
	v_mov_b32_e32 v2, v0
	v_mov_b32_e32 v3, v0
	v_mov_b32_e32 v4, v0
	v_mov_b32_e32 v5, v0
	v_mov_b32_e32 v6, v0
	v_mov_b32_e32 v7, v0
	v_mov_b32_e32 v8, v0
	v_mov_b32_e32 v9, v0
	v_mov_b32_e32 v10, v0
	v_mov_b32_e32 v11, v0
	v_mov_b32_e32 v12, v0
	v_mov_b32_e32 v13, v0
	v_mov_b32_e32 v14, v0
	v_mov_b32_e32 v15, v0
	v_mov_b32_e32 v17, v16
	v_mov_b32_e32 v18, v16
	v_mov_b32_e32 v19, v16
	v_mov_b32_e32 v20, v16
	v_mov_b32_e32 v21, v16
	v_mov_b32_e32 v22, v16
	v_mov_b32_e32 v23, v16
	v_mov_b32_e32 v24, v16
	v_mov_b32_e32 v25, v16
	v_mov_b32_e32 v26, v16
	v_mov_b32_e32 v27, v16
	v_mov_b32_e32 v28, v16
	v_mov_b32_e32 v29, v16
	v_mov_b32_e32 v30, v16
	v_mov_b32_e32 v31, v16
	v_lshl_add_u64 v[142:143], s[42:43], 0, v[36:37]
	s_movk_i32 s28, 0x100
	v_mov_b32_e32 v222, 0
	s_mov_b64 s[44:45], 0
	s_movk_i32 s25, 0x700
	v_add_u32_e32 v165, 0x15c00, v32
	v_add_u32_e32 v166, v44, v52
	v_add_u32_e32 v168, v45, v53
	v_add_u32_e32 v169, v45, v54
	v_add_u32_e32 v170, v45, v55
	v_add_u32_e32 v171, v45, v56
	v_add_u32_e32 v172, v47, v46
	v_add_u32_e32 v173, v48, v46
	v_add_u32_e32 v174, v49, v57
	v_add_u32_e32 v175, v50, v58
	v_add_u32_e32 v176, v49, v59
	v_add_u32_e32 v177, v50, v60
	v_add_u32_e32 v178, v49, v61
	v_add_u32_e32 v179, v50, v62
	v_add_u32_e32 v193, v50, v128
	v_add_u32_e32 v194, v49, v130
	v_add_u32_e32 v195, v50, v131
	v_add_u32_e32 v196, v49, v133
	v_add_u32_e32 v197, v50, v134
	v_add_u32_e32 v198, v49, v146
	v_add_u32_e32 v199, v50, v147
	v_add_u32_e32 v200, v49, v148
	v_add_u32_e32 v201, v50, v149
	v_add_u32_e32 v202, v49, v162
	v_add_u32_e32 v203, v50, v163
	v_add_u32_e32 v204, v49, v204
	v_add_u32_e32 v205, v50, v205
	v_add_u32_e32 v206, v51, v206
	v_add_u32_e32 v207, v51, v207
	v_add_u32_e32 v208, v51, v208
	v_add_u32_e32 v209, v51, v63
	v_add_u32_e32 v210, v51, v210
	v_add_u32_e32 v211, v51, v211
	v_add_u32_e32 v212, v51, v212
	v_add_u32_e32 v216, v51, v129
	v_add_u32_e32 v217, v51, v132
	v_add_u32_e32 v218, v51, v135
	v_add_u32_e32 v219, v51, v219
	v_add_u32_e32 v220, v51, v220
	v_add_u32_e32 v221, v51, v221
	v_mov_b64_e32 v[112:113], v[64:65]
	v_mov_b64_e32 v[116:117], v[64:65]
	v_mov_b64_e32 v[120:121], v[64:65]
	v_mov_b64_e32 v[124:125], v[64:65]
	s_mov_b32 s46, 0
	s_mov_b32 s29, 0
	v_lshrrev_b32_e32 v32, 8, v167
	v_mul_u32_u24_e32 v33, 0x3600, v32
	v_add_u32_e32 v168, v168, v33
	v_add_u32_e32 v169, v169, v33
	v_add_u32_e32 v170, v170, v33
	v_add_u32_e32 v171, v171, v33
	v_add_u32_e32 v169, 0xffffee00, v169
	v_add_u32_e32 v170, 0xffffdc00, v170
; #define LAS __attribute__((address_space(3)))
; #define LDS_BARRIER() do { asm volatile("s_waitcnt lgkmcnt(0)" ::: "memory"); __builtin_amdgcn_s_barrier(); asm volatile("" ::: "memory"); } while (0)
; template <int dir>
; __device__ __forceinline__ void lru_pass(LAS unsigned char* lds, const Params& P, int b, int h, int q, bool dry) {
;     ...
;             for (int i = 0; i < NIN; ++i) { const int id = tid + i * NTHREADS;
;                 if (dir == 0) *(LAS u32x4*)(TIN + (id >> 2) * IO_NP + (id & 3) * 16) = inr[i];
;                 else *(LAS u32x4*)(TIN + (id >> 3) * IO_WP + (id & 7) * 16) = inr[i]; }
;             LruTile nxt = cur;
;             if (sc < 8) { nxt = lru_tile(Z, ZC, b, h, dir, sc + 1); lru_load_rows(rows, nxt, tr, cgp);
; #pragma unroll
;                 for (int i = 0; i < NIN; ++i) { const int id = tid + i * NTHREADS;
;                     if (dir == 0) inr[i] = *(const u32x4*)(Zg + (size_t)(nxt.t0 + (id >> 2)) * 128 + (id & 3) * 8);
;                     else inr[i] = *(const u32x4*)(Hg + (size_t)(nxt.t0 + (id >> 3)) * DM + (id & 7) * 4); } }
;             LDS_BARRIER();
;             if (sc >= 2) {
;                 if (dir == 0) {
; #pragma unroll
;                     for (int i = 0; i < 4; ++i) { const int id = tid + i * NTHREADS; *(u32x4*)(Hg + (size_t)(t0_prev + (id >> 3)) * DM + (id & 7) * 4) = *(const LAS u32x4*)(TOUT + (id >> 3) * IO_WP + (id & 7) * 16); }
;                 } else if (!dry) {
; #pragma unroll
;                     for (int i = 0; i < 2; ++i) { const int id = tid + i * NTHREADS; *(u32x4*)(Z + ZSLAB(8 + h, (size_t)b * SEQ + t0_prev + (id >> 2)) + q * 32 + (id & 3) * 8) = *(const LAS u32x4*)(TOUT + (id >> 2) * IO_NP + (id & 3) * 16); }
;                 }
;             }
;             f32x16 zr, zi;
; #pragma unroll
;             for (int v = 0; v < 16; ++v) { zr[v] = br; zi[v] = bi; }
;             const int sbase = 32 * wid + 16 * g;
;             { const int sl = 32 * wid + s_i; const int tlA = dir == 0 ? sl : 255 - sl;
	v_add_u32_e32 v171, 0xffffca00, v171
	v_mul_u32_u24_e32 v66, 0x60000, v32
	v_mov_b32_e32 v67, 0
	v_lshl_add_u64 v[142:143], v[66:67], 0, v[142:143]
	v_lshl_add_u64 v[252:253], v[66:67], 0, v[252:253]
	v_lshl_add_u64 v[154:155], v[66:67], 0, v[154:155]
	v_lshl_add_u64 v[150:151], v[66:67], 0, v[150:151]
	s_mov_b32 s19, -1
	s_mov_b32 s18, 0xfffe0000
	v_lshl_add_u64 v[252:253], v[252:253], 0, s[18:19]
	s_mov_b32 s18, 0xfffc0000
	v_lshl_add_u64 v[154:155], v[154:155], 0, s[18:19]
	s_mov_b32 s18, 0xfffa0000
	v_lshl_add_u64 v[150:151], v[150:151], 0, s[18:19]
	v_mul_u32_u24_e32 v33, 0x1400, v32
	v_add_u32_e32 v164, v164, v33
	v_add_u32_e32 v152, v152, v33
	v_add_u32_e32 v152, 0xffffec00, v152
	v_lshlrev_b32_e32 v33, 6, v32
	v_add_u32_e32 v140, v140, v33
	v_add_u32_e32 v138, v138, v33
	v_add_u32_e32 v138, 0xffffffc0, v138
	v_lshrrev_b32_e32 v33, 6, v167
	s_nop 1
	v_readfirstlane_b32 s18, v33
	s_lshl_b32 s19, s18, 6
	s_sub_i32 s19, s19, 0xe0
	s_mul_i32 s20, s19, 0x110
	v_add_u32_e32 v172, s20, v172
	v_add_u32_e32 v174, s20, v174
	v_add_u32_e32 v176, s20, v176
	v_add_u32_e32 v178, s20, v178
	v_add_u32_e32 v180, s20, v180
	v_add_u32_e32 v182, s20, v182
	v_add_u32_e32 v184, s20, v184
	v_add_u32_e32 v186, s20, v186
	v_add_u32_e32 v188, s20, v188
	v_add_u32_e32 v190, s20, v190
	v_add_u32_e32 v192, s20, v192
	v_add_u32_e32 v194, s20, v194
	v_add_u32_e32 v196, s20, v196
	v_add_u32_e32 v198, s20, v198
	v_add_u32_e32 v200, s20, v200
	v_add_u32_e32 v202, s20, v202
	v_add_u32_e32 v204, s20, v204
	s_mul_i32 s20, s19, 0x90
	v_add_u32_e32 v175, s20, v175
	v_add_u32_e32 v177, s20, v177
	v_add_u32_e32 v179, s20, v179
	v_add_u32_e32 v181, s20, v181
	v_add_u32_e32 v183, s20, v183
	v_add_u32_e32 v185, s20, v185
	v_add_u32_e32 v187, s20, v187
	v_add_u32_e32 v189, s20, v189
	v_add_u32_e32 v191, s20, v191
	v_add_u32_e32 v193, s20, v193
	v_add_u32_e32 v195, s20, v195
	v_add_u32_e32 v197, s20, v197
	v_add_u32_e32 v199, s20, v199
	v_add_u32_e32 v201, s20, v201
	v_add_u32_e32 v203, s20, v203
	v_add_u32_e32 v205, s20, v205
	s_mul_i32 s20, s19, 0x50
	v_add_u32_e32 v206, s20, v206
	v_add_u32_e32 v207, s20, v207
	v_add_u32_e32 v208, s20, v208
	v_add_u32_e32 v209, s20, v209
	v_add_u32_e32 v210, s20, v210
	v_add_u32_e32 v211, s20, v211
	v_add_u32_e32 v212, s20, v212
	v_add_u32_e32 v213, s20, v213
	v_add_u32_e32 v214, s20, v214
	v_add_u32_e32 v215, s20, v215
	v_add_u32_e32 v216, s20, v216
	v_add_u32_e32 v217, s20, v217
	v_add_u32_e32 v218, s20, v218
	v_add_u32_e32 v219, s20, v219
	v_add_u32_e32 v220, s20, v220
	v_add_u32_e32 v221, s20, v221
	s_lshl_b32 s20, s18, 1
	s_sub_i32 s20, 7, s20
	s_lshl_b32 s20, s20, 8
	v_add_u32_e32 v254, s20, v254
	s_sub_i32 s18, 7, s18
	s_lshr_b32 s101, s18, 2
	s_or_b32 s19, s18, 4
	s_cmp_eq_u32 s19, 7
	s_cselect_b64 s[0:1], -1, 0
	s_cmp_eq_u32 s19, 6
	s_cselect_b64 s[16:17], -1, 0
	s_cmp_eq_u32 s19, 5
	s_cselect_b64 s[4:5], -1, 0
	s_cmp_eq_u32 s19, 4
	s_cselect_b64 s[8:9], -1, 0
	s_cmp_eq_u32 s19, 3
	s_cselect_b64 s[10:11], -1, 0
	s_cmp_eq_u32 s19, 2
	s_cselect_b64 s[12:13], -1, 0
	s_cmp_eq_u32 s19, 1
	s_cselect_b64 s[14:15], -1, 0
	s_mov_b32 s98, 0
	s_cmp_eq_u32 s101, 0
	s_cselect_b32 s99, 0x14400, 0
	s_cselect_b32 s100, 0, 0x400
	v_add_u32_e32 v33, 0x14000, v254
	v_mov_b32_e32 v66, 1.0
	v_mov_b32_e32 v67, 0
	ds_write2_b32 v33, v66, v67 offset1:32
	v_lshrrev_b32_e32 v66, 8, v167
	v_lshlrev_b32_e32 v66, 7, v66
	v_bfe_u32 v67, v167, 2, 6
	v_add_u32_e32 v66, v66, v67
	v_and_b32_e32 v67, 3, v167
	v_lshlrev_b32_e32 v67, 4, v67
	v_mul_u32_u24_e32 v168, 0x90, v66
	v_lshl_add_u32 v168, v67, 1, v168
	v_add_u32_e32 v168, s95, v168
	v_add_u32_e32 v169, 0x2400, v168
	v_lshl_add_u32 v66, v66, 8, v67
	v_mov_b32_e32 v67, 0
	s_lshr_b32 s18, s2, 5
	s_add_i32 s18, s18, 8
	s_lshl_b32 s18, s18, 22
	s_add_u32 s18, s18, 0x5470000
	s_and_b32 s19, s2, 7
	s_lshl_b32 s19, s19, 19
	s_add_u32 s18, s18, s19
	s_bfe_u32 s19, s2, 0x20003
	s_lshl_b32 s19, s19, 6
	s_add_u32 s18, s18, s19
	s_add_u32 s18, s22, s18
	s_addc_u32 s19, s23, 0
	v_lshl_add_u64 v[142:143], s[18:19], 0, v[66:67]
	s_mov_b32 s20, 0x4000
	s_mov_b32 s21, 0
	v_lshl_add_u64 v[252:253], v[142:143], 0, s[20:21]
	s_mov_b32 s40, 0x6000000
	s_mov_b32 s41, 0
	s_cmp_eq_u32 s101, 0
	s_cbranch_scc1 .Lpp_b_nox
	s_waitcnt lgkmcnt(0)
	s_barrier

; #define LAS __attribute__((address_space(3)))
; __device__ __forceinline__ unsigned cvt_pk_bf16(float lo, float hi) { unsigned r; asm volatile("v_cvt_pk_bf16_f32 %0, %1, %2" : "=v"(r) : "v"(lo), "v"(hi)); return r; }
; __device__ __forceinline__ float bf_lo(unsigned u) { return __uint_as_float(u << 16); }
; __device__ __forceinline__ float bf_hi(unsigned u) { return __uint_as_float(u & 0xffff0000u); }
; template <int dir>
; __device__ __forceinline__ void lru_pass(LAS unsigned char* lds, const Params& P, int b, int h, int q, bool dry) {
;     ...
;             f32x2 cw2[4][4], cb2[4];
; #pragma unroll
;             for (int k = 0; k < 5; ++k) { const f32x4 a = *(const LAS f32x4*)(CWL + k * 128 + cgp * 8), c2 = *(const LAS f32x4*)(CWL + k * 128 + cgp * 8 + 4);
;                 if (k < 4) { cw2[k][0] = (f32x2){a[0], a[1]}; cw2[k][1] = (f32x2){a[2], a[3]}; cw2[k][2] = (f32x2){c2[0], c2[1]}; cw2[k][3] = (f32x2){c2[2], c2[3]}; }
;                 else { cb2[0] = (f32x2){a[0], a[1]}; cb2[1] = (f32x2){a[2], a[3]}; cb2[2] = (f32x2){c2[0], c2[1]}; cb2[3] = (f32x2){c2[2], c2[3]}; } }
; #pragma unroll
;             for (int j = 0; j < 8; ++j) {
;                 f32x2 o0 = cb2[0], o1 = cb2[1], o2 = cb2[2], o3 = cb2[3];
; #pragma unroll
;                 for (int k = 0; k < 4; ++k) { const u32x4 rr = rows[j + k];
;                     o0 = cw2[k][0] * (f32x2){bf_lo(rr.x), bf_hi(rr.x)} + o0; o1 = cw2[k][1] * (f32x2){bf_lo(rr.y), bf_hi(rr.y)} + o1;
;                     o2 = cw2[k][2] * (f32x2){bf_lo(rr.z), bf_hi(rr.z)} + o2; o3 = cw2[k][3] * (f32x2){bf_lo(rr.w), bf_hi(rr.w)} + o3; }
;                 u32x4 w; w.x = cvt_pk_bf16(o0[0], o0[1]); w.y = cvt_pk_bf16(o1[0], o1[1]); w.z = cvt_pk_bf16(o2[0], o2[1]); w.w = cvt_pk_bf16(o3[0], o3[1]);
;                 *(LAS u32x4*)(XC + (tr * 8 + j) * XC_PITCH + cgp * 16) = w;
;             }
.Lmsk_b_j:
	ds_read_b128 v[60:63], v165
	ds_read_b128 v[52:55], v165 offset:256
	ds_read_b128 v[44:47], v165 offset:768
	ds_read_b128 v[56:59], v165 offset:512
	ds_read_b128 v[40:43], v165 offset:1280
	ds_read_b128 v[48:51], v165 offset:1024
	ds_read_b128 v[128:131], v165 offset:2304
	ds_read_b128 v[132:135], v165 offset:2048
	ds_read_b128 v[32:35], v165 offset:1792
	ds_read_b128 v[36:39], v165 offset:1536
	v_lshlrev_b32_e32 v66, 16, v68
	v_and_b32_e32 v67, 0xffff0000, v68
	v_lshlrev_b32_e32 v148, 16, v70
	v_and_b32_e32 v149, 0xffff0000, v70
	s_waitcnt lgkmcnt(2)
	v_pk_fma_f32 v[66:67], v[60:61], v[66:67], v[132:133]
	v_lshlrev_b32_e32 v146, 16, v69
	v_and_b32_e32 v147, 0xffff0000, v69
	v_pk_fma_f32 v[148:149], v[52:53], v[148:149], v[128:129]
	v_lshlrev_b32_e32 v224, 16, v71
	v_and_b32_e32 v225, 0xffff0000, v71
	v_lshlrev_b32_e32 v228, 16, v72
	v_and_b32_e32 v229, 0xffff0000, v72
	v_lshlrev_b32_e32 v232, 16, v74
	v_and_b32_e32 v233, 0xffff0000, v74
	v_pk_fma_f32 v[146:147], v[62:63], v[146:147], v[134:135]
	v_pk_fma_f32 v[224:225], v[54:55], v[224:225], v[130:131]
	v_pk_fma_f32 v[66:67], v[56:57], v[228:229], v[66:67]
	v_lshlrev_b32_e32 v230, 16, v73
	v_and_b32_e32 v231, 0xffff0000, v73
	v_pk_fma_f32 v[148:149], v[44:45], v[232:233], v[148:149]
	v_lshlrev_b32_e32 v234, 16, v75
	v_and_b32_e32 v235, 0xffff0000, v75
	v_lshlrev_b32_e32 v236, 16, v76
	v_and_b32_e32 v237, 0xffff0000, v76
	v_lshlrev_b32_e32 v240, 16, v78
	v_and_b32_e32 v241, 0xffff0000, v78
	v_pk_fma_f32 v[146:147], v[58:59], v[230:231], v[146:147]
	v_pk_fma_f32 v[224:225], v[46:47], v[234:235], v[224:225]
	v_pk_fma_f32 v[66:67], v[48:49], v[236:237], v[66:67]
	v_lshlrev_b32_e32 v238, 16, v77
	v_and_b32_e32 v239, 0xffff0000, v77
	v_pk_fma_f32 v[148:149], v[40:41], v[240:241], v[148:149]
	v_lshlrev_b32_e32 v242, 16, v79
	v_and_b32_e32 v243, 0xffff0000, v79
	v_lshlrev_b32_e32 v244, 16, v80
	v_and_b32_e32 v245, 0xffff0000, v80
	v_lshlrev_b32_e32 v248, 16, v82
	v_and_b32_e32 v249, 0xffff0000, v82
	v_pk_fma_f32 v[146:147], v[50:51], v[238:239], v[146:147]
	v_pk_fma_f32 v[224:225], v[42:43], v[242:243], v[224:225]
	s_waitcnt lgkmcnt(0)
	v_pk_fma_f32 v[66:67], v[36:37], v[244:245], v[66:67]
	v_lshlrev_b32_e32 v246, 16, v81
	v_and_b32_e32 v247, 0xffff0000, v81
	v_pk_fma_f32 v[148:149], v[32:33], v[248:249], v[148:149]
	v_lshlrev_b32_e32 v250, 16, v83
	v_and_b32_e32 v251, 0xffff0000, v83
	v_pk_fma_f32 v[146:147], v[38:39], v[246:247], v[146:147]
	v_pk_fma_f32 v[162:163], v[34:35], v[250:251], v[224:225]
	v_cvt_pk_bf16_f32 v224, v66, v67
	v_cvt_pk_bf16_f32 v225, v146, v147
	v_cvt_pk_bf16_f32 v226, v148, v149
	v_pk_fma_f32 v[66:67], v[60:61], v[228:229], v[132:133]
	v_pk_fma_f32 v[148:149], v[52:53], v[232:233], v[128:129]
	v_pk_fma_f32 v[146:147], v[62:63], v[230:231], v[134:135]
	v_pk_fma_f32 v[66:67], v[56:57], v[236:237], v[66:67]
	v_pk_fma_f32 v[148:149], v[44:45], v[240:241], v[148:149]
	v_pk_fma_f32 v[146:147], v[58:59], v[238:239], v[146:147]
	v_pk_fma_f32 v[66:67], v[48:49], v[244:245], v[66:67]
	v_pk_fma_f32 v[148:149], v[40:41], v[248:249], v[148:149]
	v_lshlrev_b32_e32 v228, 16, v84
	v_and_b32_e32 v229, 0xffff0000, v84
	v_lshlrev_b32_e32 v232, 16, v86
	v_and_b32_e32 v233, 0xffff0000, v86
	v_cvt_pk_bf16_f32 v227, v162, v163
	v_pk_fma_f32 v[162:163], v[54:55], v[234:235], v[130:131]
	v_pk_fma_f32 v[146:147], v[50:51], v[246:247], v[146:147]
	v_pk_fma_f32 v[66:67], v[36:37], v[228:229], v[66:67]
	v_lshlrev_b32_e32 v230, 16, v85
	v_and_b32_e32 v231, 0xffff0000, v85
	v_pk_fma_f32 v[148:149], v[32:33], v[232:233], v[148:149]
	ds_write_b128 v166, v[224:227]
	v_pk_fma_f32 v[162:163], v[46:47], v[242:243], v[162:163]
	v_pk_fma_f32 v[146:147], v[38:39], v[230:231], v[146:147]
	v_cvt_pk_bf16_f32 v224, v66, v67
	v_pk_fma_f32 v[66:67], v[60:61], v[236:237], v[132:133]
	v_cvt_pk_bf16_f32 v225, v146, v147
	v_cvt_pk_bf16_f32 v226, v148, v149
	v_pk_fma_f32 v[148:149], v[52:53], v[240:241], v[128:129]
	v_pk_fma_f32 v[162:163], v[42:43], v[250:251], v[162:163]
	v_lshlrev_b32_e32 v234, 16, v87
	v_and_b32_e32 v235, 0xffff0000, v87
	v_pk_fma_f32 v[146:147], v[62:63], v[238:239], v[134:135]
	v_pk_fma_f32 v[66:67], v[56:57], v[244:245], v[66:67]
	v_pk_fma_f32 v[148:149], v[44:45], v[248:249], v[148:149]
	v_pk_fma_f32 v[162:163], v[34:35], v[234:235], v[162:163]
	v_pk_fma_f32 v[146:147], v[58:59], v[246:247], v[146:147]
	v_pk_fma_f32 v[66:67], v[48:49], v[228:229], v[66:67]
	v_pk_fma_f32 v[148:149], v[40:41], v[232:233], v[148:149]
	v_lshlrev_b32_e32 v236, 16, v88
	v_and_b32_e32 v237, 0xffff0000, v88
	v_lshlrev_b32_e32 v240, 16, v90
	v_and_b32_e32 v241, 0xffff0000, v90
	v_cvt_pk_bf16_f32 v227, v162, v163
	v_pk_fma_f32 v[162:163], v[54:55], v[242:243], v[130:131]
	v_pk_fma_f32 v[146:147], v[50:51], v[230:231], v[146:147]
	v_pk_fma_f32 v[66:67], v[36:37], v[236:237], v[66:67]
	v_lshlrev_b32_e32 v238, 16, v89
	v_and_b32_e32 v239, 0xffff0000, v89
	v_pk_fma_f32 v[148:149], v[32:33], v[240:241], v[148:149]
	ds_write_b128 v166, v[224:227] offset:272
	v_pk_fma_f32 v[162:163], v[46:47], v[250:251], v[162:163]
	v_pk_fma_f32 v[146:147], v[38:39], v[238:239], v[146:147]
	v_cvt_pk_bf16_f32 v224, v66, v67
	v_pk_fma_f32 v[66:67], v[60:61], v[244:245], v[132:133]
	v_cvt_pk_bf16_f32 v225, v146, v147
	v_cvt_pk_bf16_f32 v226, v148, v149
	v_pk_fma_f32 v[148:149], v[52:53], v[248:249], v[128:129]
	v_pk_fma_f32 v[162:163], v[42:43], v[234:235], v[162:163]
	v_lshlrev_b32_e32 v242, 16, v91
	v_and_b32_e32 v243, 0xffff0000, v91
	v_pk_fma_f32 v[146:147], v[62:63], v[246:247], v[134:135]
	v_pk_fma_f32 v[66:67], v[56:57], v[228:229], v[66:67]
	v_pk_fma_f32 v[148:149], v[44:45], v[232:233], v[148:149]
; #define LAS __attribute__((address_space(3)))
; __device__ __forceinline__ unsigned cvt_pk_bf16(float lo, float hi) { unsigned r; asm volatile("v_cvt_pk_bf16_f32 %0, %1, %2" : "=v"(r) : "v"(lo), "v"(hi)); return r; }
; __device__ __forceinline__ float bf_lo(unsigned u) { return __uint_as_float(u << 16); }
; __device__ __forceinline__ float bf_hi(unsigned u) { return __uint_as_float(u & 0xffff0000u); }
; template <int dir>
; __device__ __forceinline__ void lru_pass(LAS unsigned char* lds, const Params& P, int b, int h, int q, bool dry) {
;     ...
;             for (int j = 0; j < 8; ++j) {
;                 f32x2 o0 = cb2[0], o1 = cb2[1], o2 = cb2[2], o3 = cb2[3];
; #pragma unroll
;                 for (int k = 0; k < 4; ++k) { const u32x4 rr = rows[j + k];
;                     o0 = cw2[k][0] * (f32x2){bf_lo(rr.x), bf_hi(rr.x)} + o0; o1 = cw2[k][1] * (f32x2){bf_lo(rr.y), bf_hi(rr.y)} + o1;
;                     o2 = cw2[k][2] * (f32x2){bf_lo(rr.z), bf_hi(rr.z)} + o2; o3 = cw2[k][3] * (f32x2){bf_lo(rr.w), bf_hi(rr.w)} + o3; }
;                 u32x4 w; w.x = cvt_pk_bf16(o0[0], o0[1]); w.y = cvt_pk_bf16(o1[0], o1[1]); w.z = cvt_pk_bf16(o2[0], o2[1]); w.w = cvt_pk_bf16(o3[0], o3[1]);
;                 *(LAS u32x4*)(XC + (tr * 8 + j) * XC_PITCH + cgp * 16) = w;
;             }
	v_pk_fma_f32 v[162:163], v[34:35], v[242:243], v[162:163]
	v_pk_fma_f32 v[146:147], v[58:59], v[230:231], v[146:147]
	v_pk_fma_f32 v[66:67], v[48:49], v[236:237], v[66:67]
	v_pk_fma_f32 v[148:149], v[40:41], v[240:241], v[148:149]
	v_lshlrev_b32_e32 v244, 16, v92
	v_and_b32_e32 v245, 0xffff0000, v92
	v_lshlrev_b32_e32 v248, 16, v94
	v_and_b32_e32 v249, 0xffff0000, v94
	v_cvt_pk_bf16_f32 v227, v162, v163
	v_pk_fma_f32 v[162:163], v[54:55], v[250:251], v[130:131]
	v_pk_fma_f32 v[146:147], v[50:51], v[238:239], v[146:147]
	v_pk_fma_f32 v[66:67], v[36:37], v[244:245], v[66:67]
	v_lshlrev_b32_e32 v246, 16, v93
	v_and_b32_e32 v247, 0xffff0000, v93
	v_pk_fma_f32 v[148:149], v[32:33], v[248:249], v[148:149]
	ds_write_b128 v166, v[224:227] offset:544
	v_pk_fma_f32 v[162:163], v[46:47], v[234:235], v[162:163]
	v_pk_fma_f32 v[146:147], v[38:39], v[246:247], v[146:147]
	v_cvt_pk_bf16_f32 v224, v66, v67
	v_pk_fma_f32 v[66:67], v[60:61], v[228:229], v[132:133]
	v_cvt_pk_bf16_f32 v225, v146, v147
	v_cvt_pk_bf16_f32 v226, v148, v149
	v_pk_fma_f32 v[148:149], v[52:53], v[232:233], v[128:129]
	v_pk_fma_f32 v[162:163], v[42:43], v[242:243], v[162:163]
	v_lshlrev_b32_e32 v250, 16, v95
	v_and_b32_e32 v251, 0xffff0000, v95
	v_pk_fma_f32 v[146:147], v[62:63], v[230:231], v[134:135]
	v_pk_fma_f32 v[66:67], v[56:57], v[236:237], v[66:67]
	v_pk_fma_f32 v[148:149], v[44:45], v[240:241], v[148:149]
	v_pk_fma_f32 v[162:163], v[34:35], v[250:251], v[162:163]
	v_pk_fma_f32 v[146:147], v[58:59], v[238:239], v[146:147]
	v_pk_fma_f32 v[66:67], v[48:49], v[244:245], v[66:67]
	v_pk_fma_f32 v[148:149], v[40:41], v[248:249], v[148:149]
	v_lshlrev_b32_e32 v228, 16, v96
	v_and_b32_e32 v229, 0xffff0000, v96
	v_lshlrev_b32_e32 v232, 16, v98
	v_and_b32_e32 v233, 0xffff0000, v98
	v_cvt_pk_bf16_f32 v227, v162, v163
	v_pk_fma_f32 v[162:163], v[54:55], v[234:235], v[130:131]
	v_pk_fma_f32 v[146:147], v[50:51], v[246:247], v[146:147]
	v_pk_fma_f32 v[66:67], v[36:37], v[228:229], v[66:67]
	v_lshlrev_b32_e32 v230, 16, v97
	v_and_b32_e32 v231, 0xffff0000, v97
	v_pk_fma_f32 v[148:149], v[32:33], v[232:233], v[148:149]
	ds_write_b128 v166, v[224:227] offset:816
	v_pk_fma_f32 v[162:163], v[46:47], v[242:243], v[162:163]
	v_pk_fma_f32 v[146:147], v[38:39], v[230:231], v[146:147]
	v_cvt_pk_bf16_f32 v224, v66, v67
	v_pk_fma_f32 v[66:67], v[60:61], v[236:237], v[132:133]
	v_cvt_pk_bf16_f32 v225, v146, v147
	v_cvt_pk_bf16_f32 v226, v148, v149
	v_pk_fma_f32 v[148:149], v[52:53], v[240:241], v[128:129]
	v_pk_fma_f32 v[162:163], v[42:43], v[250:251], v[162:163]
	v_lshlrev_b32_e32 v234, 16, v99
	v_and_b32_e32 v235, 0xffff0000, v99
	v_pk_fma_f32 v[146:147], v[62:63], v[238:239], v[134:135]
	v_pk_fma_f32 v[66:67], v[56:57], v[244:245], v[66:67]
	v_pk_fma_f32 v[148:149], v[44:45], v[248:249], v[148:149]
	v_pk_fma_f32 v[162:163], v[34:35], v[234:235], v[162:163]
	v_pk_fma_f32 v[146:147], v[58:59], v[246:247], v[146:147]
	v_pk_fma_f32 v[66:67], v[48:49], v[228:229], v[66:67]
	v_pk_fma_f32 v[148:149], v[40:41], v[232:233], v[148:149]
	v_lshlrev_b32_e32 v236, 16, v100
	v_and_b32_e32 v237, 0xffff0000, v100
	v_lshlrev_b32_e32 v240, 16, v102
	v_and_b32_e32 v241, 0xffff0000, v102
	v_cvt_pk_bf16_f32 v227, v162, v163
	v_pk_fma_f32 v[162:163], v[54:55], v[242:243], v[130:131]
	v_pk_fma_f32 v[146:147], v[50:51], v[230:231], v[146:147]
	v_pk_fma_f32 v[66:67], v[36:37], v[236:237], v[66:67]
	v_lshlrev_b32_e32 v238, 16, v101
	v_and_b32_e32 v239, 0xffff0000, v101
	v_pk_fma_f32 v[148:149], v[32:33], v[240:241], v[148:149]
	s_and_b64 s[18:19], s[18:19], s[20:21]
	ds_write_b128 v166, v[224:227] offset:1088
	v_pk_fma_f32 v[162:163], v[46:47], v[250:251], v[162:163]
	v_pk_fma_f32 v[146:147], v[38:39], v[238:239], v[146:147]
	v_cvt_pk_bf16_f32 v224, v66, v67
	v_pk_fma_f32 v[66:67], v[60:61], v[244:245], v[132:133]
	v_cvt_pk_bf16_f32 v225, v146, v147
	v_cvt_pk_bf16_f32 v226, v148, v149
	v_pk_fma_f32 v[148:149], v[52:53], v[248:249], v[128:129]
	v_pk_fma_f32 v[60:61], v[60:61], v[228:229], v[132:133]
	v_pk_fma_f32 v[52:53], v[52:53], v[232:233], v[128:129]
	s_waitcnt vmcnt(0)
; template <int dir>
; __device__ __forceinline__ void lru_pass(LAS unsigned char* lds, const Params& P, int b, int h, int q, bool dry) {
;     ...
;             for (int j = 0; j < 11; ++j) { if (j != 0 && j < 9) continue;
;                 const int t = t0 + tr * 8 - 1 + j; if (t < 0 || t >= cur.L) rows[j] = (u32x4){0u, 0u, 0u, 0u}; }
;             f32x2 cw2[4][4], cb2[4];
; #pragma unroll
;             for (int k = 0; k < 5; ++k) { const f32x4 a = *(const LAS f32x4*)(CWL + k * 128 + cgp * 8), c2 = *(const LAS f32x4*)(CWL + k * 128 + cgp * 8 + 4);
;                 if (k < 4) { cw2[k][0] = (f32x2){a[0], a[1]}; cw2[k][1] = (f32x2){a[2], a[3]}; cw2[k][2] = (f32x2){c2[0], c2[1]}; cw2[k][3] = (f32x2){c2[2], c2[3]}; }
;                 else { cb2[0] = (f32x2){a[0], a[1]}; cb2[1] = (f32x2){a[2], a[3]}; cb2[2] = (f32x2){c2[0], c2[1]}; cb2[3] = (f32x2){c2[2], c2[3]}; } }
; #pragma unroll
;             for (int j = 0; j < 8; ++j) {
;                 f32x2 o0 = cb2[0], o1 = cb2[1], o2 = cb2[2], o3 = cb2[3];
; #pragma unroll
;                 for (int k = 0; k < 4; ++k) { const u32x4 rr = rows[j + k];
;                     o0 = cw2[k][0] * (f32x2){bf_lo(rr.x), bf_hi(rr.x)} + o0; o1 = cw2[k][1] * (f32x2){bf_lo(rr.y), bf_hi(rr.y)} + o1;
;                     o2 = cw2[k][2] * (f32x2){bf_lo(rr.z), bf_hi(rr.z)} + o2; o3 = cw2[k][3] * (f32x2){bf_lo(rr.w), bf_hi(rr.w)} + o3; }
;                 u32x4 w; w.x = cvt_pk_bf16(o0[0], o0[1]); w.y = cvt_pk_bf16(o1[0], o1[1]); w.z = cvt_pk_bf16(o2[0], o2[1]); w.w = cvt_pk_bf16(o3[0], o3[1]);
;                 *(LAS u32x4*)(XC + (tr * 8 + j) * XC_PITCH + cgp * 16) = w;
;             }
; #pragma unroll
;             for (int i = 0; i < NIN; ++i) { const int id = tid + i * NTHREADS;
;                 if (dir == 0) *(LAS u32x4*)(TIN + (id >> 2) * IO_NP + (id & 3) * 16) = inr[i];
;                 else *(LAS u32x4*)(TIN + (id >> 3) * IO_WP + (id & 7) * 16) = inr[i]; }
;             LruTile nxt = cur;
;             if (sc < 8) { nxt = lru_tile(Z, ZC, b, h, dir, sc + 1); lru_load_rows(rows, nxt, tr, cgp);
; #pragma unroll
;                 for (int i = 0; i < NIN; ++i) { const int id = tid + i * NTHREADS;
;                     if (dir == 0) inr[i] = *(const u32x4*)(Zg + (size_t)(nxt.t0 + (id >> 2)) * 128 + (id & 3) * 8);
;                     else inr[i] = *(const u32x4*)(Hg + (size_t)(nxt.t0 + (id >> 3)) * DM + (id & 7) * 4); } }
	v_cndmask_b32_e64 v108, 0, v108, s[18:19]
	v_pk_fma_f32 v[162:163], v[42:43], v[234:235], v[162:163]
	v_lshlrev_b32_e32 v242, 16, v103
	v_and_b32_e32 v243, 0xffff0000, v103
	v_pk_fma_f32 v[146:147], v[62:63], v[246:247], v[134:135]
	v_pk_fma_f32 v[66:67], v[56:57], v[228:229], v[66:67]
	v_pk_fma_f32 v[148:149], v[44:45], v[232:233], v[148:149]
	v_lshlrev_b32_e32 v244, 16, v104
	v_and_b32_e32 v245, 0xffff0000, v104
	v_lshlrev_b32_e32 v248, 16, v106
	v_and_b32_e32 v249, 0xffff0000, v106
	v_pk_fma_f32 v[62:63], v[62:63], v[230:231], v[134:135]
	v_pk_fma_f32 v[56:57], v[56:57], v[236:237], v[60:61]
	v_pk_fma_f32 v[44:45], v[44:45], v[240:241], v[52:53]
	v_cndmask_b32_e64 v109, 0, v109, s[18:19]
	v_pk_fma_f32 v[162:163], v[34:35], v[242:243], v[162:163]
	v_pk_fma_f32 v[146:147], v[58:59], v[230:231], v[146:147]
	v_pk_fma_f32 v[66:67], v[48:49], v[236:237], v[66:67]
	v_pk_fma_f32 v[148:149], v[40:41], v[240:241], v[148:149]
	v_lshlrev_b32_e32 v246, 16, v105
	v_and_b32_e32 v247, 0xffff0000, v105
	v_pk_fma_f32 v[58:59], v[58:59], v[238:239], v[62:63]
	v_pk_fma_f32 v[48:49], v[48:49], v[244:245], v[56:57]
	v_pk_fma_f32 v[40:41], v[40:41], v[248:249], v[44:45]
	v_lshlrev_b32_e32 v44, 16, v108
	v_and_b32_e32 v45, 0xffff0000, v108
	v_cndmask_b32_e64 v110, 0, v110, s[18:19]
	v_cvt_pk_bf16_f32 v227, v162, v163
	v_pk_fma_f32 v[162:163], v[54:55], v[250:251], v[130:131]
	v_pk_fma_f32 v[146:147], v[50:51], v[238:239], v[146:147]
	v_pk_fma_f32 v[66:67], v[36:37], v[244:245], v[66:67]
	v_pk_fma_f32 v[54:55], v[54:55], v[234:235], v[130:131]
	v_pk_fma_f32 v[50:51], v[50:51], v[246:247], v[58:59]
	v_pk_fma_f32 v[36:37], v[36:37], v[44:45], v[48:49]
	v_lshlrev_b32_e32 v44, 16, v109
	v_and_b32_e32 v45, 0xffff0000, v109
	v_cndmask_b32_e64 v111, 0, v111, s[18:19]
	v_pk_fma_f32 v[162:163], v[46:47], v[234:235], v[162:163]
	v_pk_fma_f32 v[146:147], v[38:39], v[246:247], v[146:147]
	v_lshlrev_b32_e32 v250, 16, v107
	v_and_b32_e32 v251, 0xffff0000, v107
	v_pk_fma_f32 v[46:47], v[46:47], v[242:243], v[54:55]
	v_pk_fma_f32 v[38:39], v[38:39], v[44:45], v[50:51]
	v_lshlrev_b32_e32 v44, 16, v110
	v_and_b32_e32 v45, 0xffff0000, v110
	v_pk_fma_f32 v[162:163], v[42:43], v[242:243], v[162:163]
	v_pk_fma_f32 v[148:149], v[32:33], v[248:249], v[148:149]
	v_pk_fma_f32 v[42:43], v[42:43], v[250:251], v[46:47]
	v_pk_fma_f32 v[40:41], v[32:33], v[44:45], v[40:41]
	v_lshlrev_b32_e32 v32, 16, v111
	v_and_b32_e32 v33, 0xffff0000, v111
	ds_write_b128 v166, v[224:227] offset:1360
	v_pk_fma_f32 v[162:163], v[34:35], v[250:251], v[162:163]
	v_cvt_pk_bf16_f32 v224, v66, v67
	v_cvt_pk_bf16_f32 v225, v146, v147
	v_cvt_pk_bf16_f32 v226, v148, v149
	v_pk_fma_f32 v[42:43], v[34:35], v[32:33], v[42:43]
	v_cvt_pk_bf16_f32 v227, v162, v163
	ds_write_b128 v166, v[224:227] offset:1632
	v_cvt_pk_bf16_f32 v32, v36, v37
	v_cvt_pk_bf16_f32 v33, v38, v39
	v_cvt_pk_bf16_f32 v34, v40, v41
	v_cvt_pk_bf16_f32 v35, v42, v43
	s_cmp_eq_u32 s44, 0xfff80000
	ds_write_b128 v166, v[32:35] offset:1904
	s_mov_b32 s20, 0x5040100
	s_mov_b32 s21, 0x7060302
	v_perm_b32 v232, v112, v120, s20
	v_perm_b32 v233, v112, v120, s21
	v_perm_b32 v234, v113, v121, s20
	v_perm_b32 v235, v113, v121, s21
	v_perm_b32 v236, v114, v122, s20
	v_perm_b32 v237, v114, v122, s21
	v_perm_b32 v238, v115, v123, s20
	v_perm_b32 v239, v115, v123, s21
	v_perm_b32 v240, v116, v124, s20
	v_perm_b32 v241, v116, v124, s21
	v_perm_b32 v242, v117, v125, s20
	v_perm_b32 v243, v117, v125, s21
	v_perm_b32 v244, v118, v126, s20
	v_perm_b32 v245, v118, v126, s21
	v_perm_b32 v246, v119, v127, s20
	v_perm_b32 v247, v119, v127, s21
	ds_write_b128 v168, v[232:235]
	ds_write_b128 v168, v[236:239] offset:16
	ds_write_b128 v169, v[240:243]
	ds_write_b128 v169, v[244:247] offset:16
	s_cbranch_scc1 .LBB0_308
	global_load_dwordx4 v[68:71], v[144:145], off offset:-1280
	global_load_dwordx4 v[72:75], v[144:145], off offset:-1024
	global_load_dwordx4 v[76:79], v[144:145], off offset:-768
	global_load_dwordx4 v[80:83], v[144:145], off offset:-512
	global_load_dwordx4 v[84:87], v[144:145], off offset:-256
	global_load_dwordx4 v[88:91], v[144:145], off
	global_load_dwordx4 v[92:95], v[144:145], off offset:256
	global_load_dwordx4 v[96:99], v[144:145], off offset:512
	global_load_dwordx4 v[100:103], v[144:145], off offset:768
	global_load_dwordx4 v[104:107], v[144:145], off offset:1024
	global_load_dwordx4 v[108:111], v[144:145], off offset:1280
	v_lshl_add_u64 v[32:33], v[142:143], 0, s[44:45]
	v_lshl_add_u64 v[34:35], v[252:253], 0, s[44:45]
	global_load_dwordx4 v[112:115], v[32:33], off
	global_load_dwordx4 v[116:119], v[34:35], off
	v_lshl_add_u64 v[32:33], v[32:33], 0, s[40:41]
	v_lshl_add_u64 v[34:35], v[34:35], 0, s[40:41]
	global_load_dwordx4 v[120:123], v[32:33], off sc1
	global_load_dwordx4 v[124:127], v[34:35], off sc1
	s_movk_i32 s28, 0x800
	s_mov_b32 s20, s25
	s_branch .LBB0_309
